# fused sub3(E_BR)->sub4(out-proj) without a grid barrier: per-row-panel counter signal/wait among the 8 producer workgroups (release only if an XCD census says they do not share an L2); barrier release
# speedup vs baseline: 1.0503x; 1.0181x over previous
.LBB0_18:
	s_cmpk_gt_i32 s15, 0x17f
	s_cbranch_scc1 .Lg_skip
	v_cmp_eq_u32_e64 s[98:99], 0, v127
	s_and_saveexec_b64 s[2:3], s[98:99]
	s_cbranch_execz .Lg_skip2
	s_lshl_b32 s98, s14, 2
	s_lshl_b32 s98, 1, s98
	s_lshr_b32 s99, s15, 6
	s_lshl_b32 s99, s99, 3
	s_and_b32 s8, s15, 7
	s_or_b32 s99, s99, s8
	s_lshl_b32 s99, s99, 2
	s_addk_i32 s99, 0x100
	v_mov_b32_e32 v1, s99
	v_mov_b32_e32 v2, s98
	global_atomic_add v1, v2, s[4:5]
.Lg_skip2:
	s_or_b64 exec, exec, s[2:3]
.Lg_skip:
	s_add_u32 s96, s0, 0xe0
	s_addc_u32 s97, s1, 0
	s_add_u32 s26, s4, 0x200
	s_addc_u32 s27, s5, 0
	s_add_u32 s34, s4, 0x1000
	s_addc_u32 s35, s5, 0
	s_add_u32 s2, s4, 0x1100
	s_addc_u32 s3, s5, 0
	v_writelane_b32 v254, s2, 2
	s_load_dwordx16 s[36:51], s[0:1], 0x40
	s_load_dwordx16 s[80:95], s[0:1], 0x0
	v_writelane_b32 v254, s3, 3
	s_add_u32 s2, s4, 0x1200
	s_addc_u32 s3, s5, 0
	s_add_u32 s22, s4, 0x1300
	s_addc_u32 s23, s5, 0
	v_writelane_b32 v254, s2, 4
	s_cmp_eq_u32 s14, 15
	v_mbcnt_lo_u32_b32 v0, -1, 0
	v_writelane_b32 v254, s3, 5
	s_cselect_b64 s[2:3], -1, 0
	v_writelane_b32 v254, s2, 6
	s_cmp_eq_u32 s14, 14
	s_waitcnt lgkmcnt(0)
	v_writelane_b32 v255, s80, 0
	v_writelane_b32 v254, s3, 7
	s_cselect_b64 s[2:3], -1, 0
	v_writelane_b32 v254, s2, 8
	s_cmp_eq_u32 s14, 13
	v_writelane_b32 v255, s81, 1
	v_writelane_b32 v254, s3, 9
	s_cselect_b64 s[2:3], -1, 0
	v_writelane_b32 v254, s2, 10
	s_cmp_eq_u32 s14, 12
	v_writelane_b32 v255, s82, 2
	v_writelane_b32 v254, s3, 11
	s_cselect_b64 s[2:3], -1, 0
	v_writelane_b32 v254, s2, 12
	s_cmp_eq_u32 s14, 11
	v_writelane_b32 v255, s83, 3
	v_writelane_b32 v254, s3, 13
	s_cselect_b64 s[2:3], -1, 0
	v_writelane_b32 v254, s2, 14
	s_cmp_eq_u32 s14, 10
	v_writelane_b32 v255, s84, 4
	v_writelane_b32 v254, s3, 15
	s_cselect_b64 s[2:3], -1, 0
	v_writelane_b32 v254, s2, 16
	s_cmp_eq_u32 s14, 9
	v_writelane_b32 v255, s85, 5
	v_writelane_b32 v254, s3, 17
	s_cselect_b64 s[2:3], -1, 0
	v_writelane_b32 v254, s2, 18
	s_cmp_eq_u32 s14, 8
	v_writelane_b32 v255, s86, 6
	v_writelane_b32 v254, s3, 19
	s_cselect_b64 s[2:3], -1, 0
	v_writelane_b32 v254, s2, 20
	s_cmp_eq_u32 s14, 7
	v_writelane_b32 v255, s87, 7
	v_writelane_b32 v254, s3, 21
	s_cselect_b64 s[2:3], -1, 0
	v_writelane_b32 v254, s2, 22
	s_cmp_eq_u32 s14, 6
	v_writelane_b32 v255, s88, 8
	v_writelane_b32 v254, s3, 23
	s_cselect_b64 s[2:3], -1, 0
	v_writelane_b32 v254, s2, 24
	s_cmp_eq_u32 s14, 5
	v_writelane_b32 v255, s89, 9
	v_writelane_b32 v254, s3, 25
	s_cselect_b64 s[2:3], -1, 0
	v_writelane_b32 v254, s2, 26
	s_cmp_eq_u32 s14, 4
	v_writelane_b32 v255, s90, 10
	v_writelane_b32 v254, s3, 27
	s_cselect_b64 s[2:3], -1, 0
	v_writelane_b32 v254, s2, 28
	s_cmp_eq_u32 s14, 3
	v_writelane_b32 v255, s91, 11
	v_writelane_b32 v254, s3, 29
	s_cselect_b64 s[2:3], -1, 0
	v_writelane_b32 v254, s2, 30
	s_cmp_eq_u32 s14, 2
	v_writelane_b32 v255, s92, 12
	v_writelane_b32 v254, s3, 31
	s_cselect_b64 s[2:3], -1, 0
	v_writelane_b32 v254, s2, 32
	s_cmp_eq_u32 s14, 1
	v_writelane_b32 v255, s93, 13
	v_writelane_b32 v254, s3, 33
	s_cselect_b64 s[2:3], -1, 0
	v_writelane_b32 v254, s2, 34
	s_cmp_eq_u32 s14, 0
	v_writelane_b32 v255, s94, 14
	v_writelane_b32 v254, s3, 35
	s_cselect_b64 s[2:3], -1, 0
	v_writelane_b32 v254, s2, 36
	v_writelane_b32 v255, s95, 15
	s_mov_b32 s82, s15
	v_writelane_b32 v254, s3, 37
	s_lshl_b32 s2, s14, 8
	s_add_u32 s2, s4, s2
	s_addc_u32 s3, s5, 0
	s_add_u32 s8, s2, 0x1400
	s_addc_u32 s9, s3, 0
	v_writelane_b32 v254, s8, 38
	s_add_u32 s2, s2, 0x2400
	s_addc_u32 s3, s3, 0
	v_writelane_b32 v254, s9, 39
	v_writelane_b32 v254, s2, 40
	s_load_dwordx4 s[8:11], s[0:1], 0xc0
	v_mov_b32_e32 v117, 0
	v_writelane_b32 v254, s3, 41
	s_add_u32 s2, s4, 0x3400
	s_addc_u32 s3, s5, 0
	v_writelane_b32 v254, s2, 42
	s_movk_i32 s76, 0x5000
	s_mov_b32 s75, 0x43800000
	v_writelane_b32 v254, s3, 43
	s_add_u32 s2, s4, 0x3500
	s_addc_u32 s3, s5, 0
	v_writelane_b32 v254, s2, 44
	v_mov_b32_e32 v212, 0x358637bd
	v_mbcnt_hi_u32_b32 v213, -1, v0
	v_writelane_b32 v254, s3, 45
	s_add_u32 s2, s36, 0x5a000
	v_writelane_b32 v254, s36, 46
	s_addc_u32 s3, s37, 0
	v_mov_b32_e32 v118, 0x33800000
	v_writelane_b32 v254, s37, 47
	v_writelane_b32 v254, s38, 48
	v_writelane_b32 v254, s39, 49
	v_writelane_b32 v254, s40, 50
	v_writelane_b32 v254, s41, 51
	v_writelane_b32 v254, s42, 52
	v_writelane_b32 v254, s43, 53
	v_writelane_b32 v254, s44, 54
	v_writelane_b32 v254, s45, 55
	v_writelane_b32 v254, s46, 56
	v_writelane_b32 v254, s47, 57
	v_writelane_b32 v254, s48, 58
	v_writelane_b32 v254, s49, 59
	v_writelane_b32 v254, s50, 60
	v_writelane_b32 v254, s51, 61
	s_load_dwordx16 s[48:63], s[0:1], 0x80
	v_writelane_b32 v254, s2, 62
	v_mov_b32_e32 v242, 0x3c0881c4
	v_mov_b32_e32 v219, 0xbab64f3b
	v_writelane_b32 v254, s3, 63
	s_waitcnt lgkmcnt(0)
	v_writelane_b32 v255, s48, 16
	v_mov_b32_e32 v218, 0xb0000
	v_mov_b32_e32 v220, 0xf149f2ca
	v_writelane_b32 v255, s49, 17
	v_writelane_b32 v255, s50, 18
	v_writelane_b32 v255, s51, 19
	v_writelane_b32 v255, s52, 20
	v_writelane_b32 v255, s53, 21
	v_writelane_b32 v255, s54, 22
	v_writelane_b32 v255, s55, 23
	v_writelane_b32 v255, s56, 24
	v_writelane_b32 v255, s57, 25
	v_writelane_b32 v255, s58, 26
	v_writelane_b32 v255, s59, 27
	v_writelane_b32 v255, s60, 28
	v_writelane_b32 v255, s61, 29
	v_writelane_b32 v255, s62, 30
	v_writelane_b32 v255, s63, 31
	v_writelane_b32 v255, s8, 32
	v_mov_b32_e32 v120, 0x11fe0
	v_mov_b32_e32 v221, 0xffffe400
	v_writelane_b32 v255, s9, 33
	v_writelane_b32 v255, s10, 34
	v_writelane_b32 v255, s11, 35
	v_writelane_b32 v255, s22, 36
	v_mov_b32_e32 v222, 0x1c00
	v_mov_b32_e32 v123, 0x3f2aaaaa
	v_writelane_b32 v255, s23, 37
	v_writelane_b32 v255, s26, 38
	v_not_b32_e32 v223, 63
	v_not_b32_e32 v224, 31
	v_writelane_b32 v255, s27, 39
	v_writelane_b32 v255, s34, 40
	v_mov_b32_e32 v225, 0x7fc00000
	v_mov_b32_e32 v249, 0xb00000
	v_writelane_b32 v255, s35, 41
	s_movk_i32 s79, 0x3000
	s_movk_i32 s78, 0x7000
	s_movk_i32 s77, 0xfefe
	s_mov_b32 s31, 0
	s_mov_b64 s[66:67], 0x2400
	s_mov_b64 s[28:29], 0x4000
	s_mov_b64 s[44:45], 0x2000
	s_mov_b64 s[24:25], 0x80
	s_movk_i32 s33, 0x6000
	v_writelane_b32 v255, s82, 42
	s_branch .LBB0_22

.LBB0_148:
	s_and_b32 s0, s14, -8
	s_or_b32 s0, s0, s15
	v_cmp_eq_u32_e64 s[22:23], 0, v124
	s_and_saveexec_b64 s[20:21], s[22:23]
	s_cbranch_execz .Lgw_done
	s_lshl_b32 s22, s0, 2
	s_lshl_b32 s23, s12, 8
	s_add_i32 s22, s22, s23
	s_addk_i32 s22, 0x1404
	v_mov_b32_e32 v0, s22
	s_mov_b32 s23, 0
.Lgw_spin:
	global_load_dword v1, v0, s[4:5] sc1
	s_waitcnt vmcnt(0)
	v_readfirstlane_b32 s22, v1
	s_cmp_ge_u32 s22, 8
	s_cbranch_scc1 .Lgw_got
	s_sleep 1
	s_add_i32 s23, s23, 1
	s_cmp_lt_u32 s23, 0x800
	s_cbranch_scc1 .Lgw_spin
.Lgw_got:
	buffer_inv sc1
	s_waitcnt vmcnt(0)
.Lgw_done:
	s_or_b64 exec, exec, s[20:21]
	s_barrier
	s_ashr_i32 s1, s0, 31
	s_lshl_b64 s[22:23], s[0:1], 18
	v_readfirstlane_b32 s43, v101
	v_add_u32_e32 v84, 0x400, v101
	s_and_b32 s20, s18, 0x380
	v_lshl_add_u64 v[64:65], v[96:97], 0, s[22:23]
	s_mov_b32 m0, s43
	s_mov_b64 s[22:23], 0x400
	v_readfirstlane_b32 s41, v84
	v_add_u32_e32 v85, 0x2000, v101
	s_lshl_b32 s30, s20, 11
	global_load_lds_dwordx4 v[64:65], off
	s_waitcnt lgkmcnt(0)
	v_lshl_add_u64 v[0:1], v[64:65], 0, s[22:23]
	s_mov_b32 m0, s41
	v_readfirstlane_b32 s42, v85
	v_add_u32_e32 v86, 0x2400, v101
	v_lshl_add_u64 v[66:67], v[98:99], 0, s[30:31]
	global_load_lds_dwordx4 v[0:1], off
	s_mov_b32 m0, s42
	v_readfirstlane_b32 s48, v86
	v_add_u32_e32 v80, 0x4000, v101
	global_load_lds_dwordx4 v[66:67], off
	v_lshl_add_u64 v[0:1], v[66:67], 0, s[22:23]
	s_mov_b32 m0, s48
	v_readfirstlane_b32 s38, v80
	v_add_u32_e32 v81, 0x4400, v101
	global_load_lds_dwordx4 v[0:1], off
	v_lshl_add_u64 v[0:1], v[64:65], 0, s[44:45]
	s_mov_b32 m0, s38
	v_readfirstlane_b32 s37, v81
	v_add_u32_e32 v82, 0x6000, v101
	global_load_lds_dwordx4 v[0:1], off
	v_lshl_add_u64 v[0:1], v[64:65], 0, s[66:67]
	s_mov_b32 m0, s37
	v_readfirstlane_b32 s39, v82
	v_add_u32_e32 v83, 0x6400, v101
	global_load_lds_dwordx4 v[0:1], off
	v_lshl_add_u64 v[0:1], v[66:67], 0, s[44:45]
	s_mov_b32 m0, s39
	v_readfirstlane_b32 s40, v83
	v_add_u32_e32 v76, 0x8000, v101
	global_load_lds_dwordx4 v[0:1], off
	v_lshl_add_u64 v[0:1], v[66:67], 0, s[66:67]
	s_mov_b32 m0, s40
	v_readfirstlane_b32 s34, v76
	v_add_u32_e32 v77, 0x8400, v101
	global_load_lds_dwordx4 v[0:1], off
	v_lshl_add_u64 v[0:1], v[64:65], 0, s[28:29]
	s_mov_b32 m0, s34
	s_mov_b64 s[22:23], 0x4400
	v_readfirstlane_b32 s30, v77
	v_add_u32_e32 v78, 0xa000, v101
	global_load_lds_dwordx4 v[0:1], off
	v_lshl_add_u64 v[0:1], v[64:65], 0, s[22:23]
	s_mov_b32 m0, s30
	v_readfirstlane_b32 s35, v78
	v_add_u32_e32 v79, 0xa400, v101
	global_load_lds_dwordx4 v[0:1], off
	v_lshl_add_u64 v[0:1], v[66:67], 0, s[28:29]
	s_mov_b32 m0, s35
	v_readfirstlane_b32 s36, v79
	global_load_lds_dwordx4 v[0:1], off
	v_lshl_add_u64 v[0:1], v[66:67], 0, s[22:23]
	s_mov_b32 m0, s36
	v_add_u32_e32 v68, v125, v121
	global_load_lds_dwordx4 v[0:1], off
	s_waitcnt vmcnt(8)
	v_add_u32_e32 v69, v122, v121
	v_add_u32_e32 v70, v125, v119
	v_add_u32_e32 v71, v122, v119
	s_waitcnt lgkmcnt(0)
	s_barrier
	ds_read_b128 v[0:3], v68
	ds_read_b128 v[16:19], v68 offset:2048
	ds_read_b128 v[4:7], v69 offset:8192
	ds_read_b128 v[20:23], v69 offset:10240
	ds_read_b128 v[88:91], v70
	ds_read_b128 v[92:95], v70 offset:2048
	ds_read_b128 v[152:155], v71 offset:8192
	ds_read_b128 v[156:159], v71 offset:10240
	s_mov_b64 s[22:23], 0x6000
	v_add_u32_e32 v72, 0xc000, v101
	v_lshl_add_u64 v[8:9], v[66:67], 0, s[22:23]
	v_lshl_add_u64 v[14:15], v[64:65], 0, s[22:23]
	v_readfirstlane_b32 s22, v72
	v_add_u32_e32 v73, 0xc400, v101
	s_mov_b64 s[64:65], 0x6400
	s_mov_b32 m0, s22
	v_readfirstlane_b32 s1, v73
	v_add_u32_e32 v74, 0xe000, v101
	v_lshl_add_u64 v[12:13], v[64:65], 0, s[64:65]
	global_load_lds_dwordx4 v[14:15], off
	s_mov_b32 m0, s1
	v_readfirstlane_b32 s21, v74
	v_add_u32_e32 v75, 0xe400, v101
	global_load_lds_dwordx4 v[12:13], off
	s_mov_b32 m0, s21
	v_readfirstlane_b32 s23, v75
	v_lshl_add_u64 v[10:11], v[66:67], 0, s[64:65]
	global_load_lds_dwordx4 v[8:9], off
	s_mov_b32 m0, s23
	s_nop 0
	global_load_lds_dwordx4 v[10:11], off
	s_waitcnt lgkmcnt(0)
	v_mfma_f32_32x32x16_bf16 v[32:47], v[0:3], v[4:7], 0
	s_waitcnt vmcnt(8)
	s_waitcnt lgkmcnt(0)
	s_barrier
	v_mfma_f32_32x32x16_bf16 v[48:63], v[0:3], v[20:23], 0
	v_mfma_f32_32x32x16_bf16 v[0:15], v[16:19], v[4:7], 0
	v_mfma_f32_32x32x16_bf16 v[16:31], v[16:19], v[20:23], 0
	v_mfma_f32_32x32x16_bf16 v[32:47], v[88:91], v[152:155], v[32:47]
	v_mfma_f32_32x32x16_bf16 v[48:63], v[88:91], v[156:159], v[48:63]
	v_mfma_f32_32x32x16_bf16 v[0:15], v[92:95], v[152:155], v[0:15]
	v_mfma_f32_32x32x16_bf16 v[16:31], v[92:95], v[156:159], v[16:31]
	ds_read_b128 v[88:91], v68 offset:16384
	ds_read_b128 v[92:95], v68 offset:18432
	ds_read_b128 v[152:155], v69 offset:24576
	ds_read_b128 v[156:159], v69 offset:26624
	ds_read_b128 v[160:163], v70 offset:16384
	ds_read_b128 v[164:167], v70 offset:18432
	ds_read_b128 v[168:171], v71 offset:24576
	ds_read_b128 v[172:175], v71 offset:26624
	s_mov_b64 s[64:65], 0x8000
	s_mov_b32 m0, s43
	s_mov_b64 s[68:69], 0x8400
	v_lshl_add_u64 v[182:183], v[64:65], 0, s[64:65]
	v_lshl_add_u64 v[180:181], v[64:65], 0, s[68:69]
	global_load_lds_dwordx4 v[182:183], off
	s_mov_b32 m0, s41
	v_lshl_add_u64 v[176:177], v[66:67], 0, s[64:65]
	global_load_lds_dwordx4 v[180:181], off
	s_mov_b32 m0, s42
	v_lshl_add_u64 v[178:179], v[66:67], 0, s[68:69]
	global_load_lds_dwordx4 v[176:177], off
	s_mov_b32 m0, s48
	s_nop 0
	global_load_lds_dwordx4 v[178:179], off
	s_waitcnt lgkmcnt(0)
	v_mfma_f32_32x32x16_bf16 v[32:47], v[88:91], v[152:155], v[32:47]
	s_waitcnt vmcnt(8)
	s_waitcnt lgkmcnt(0)
	s_barrier
	v_mfma_f32_32x32x16_bf16 v[48:63], v[88:91], v[156:159], v[48:63]
	v_mfma_f32_32x32x16_bf16 v[0:15], v[92:95], v[152:155], v[0:15]
	v_mfma_f32_32x32x16_bf16 v[16:31], v[92:95], v[156:159], v[16:31]
	v_mfma_f32_32x32x16_bf16 v[32:47], v[160:163], v[168:171], v[32:47]
	v_mfma_f32_32x32x16_bf16 v[48:63], v[160:163], v[172:175], v[48:63]
	v_mfma_f32_32x32x16_bf16 v[0:15], v[164:167], v[168:171], v[0:15]
	v_mfma_f32_32x32x16_bf16 v[16:31], v[164:167], v[172:175], v[16:31]
	ds_read_b128 v[88:91], v68 offset:32768
	ds_read_b128 v[92:95], v68 offset:34816
	ds_read_b128 v[152:155], v69 offset:40960
	ds_read_b128 v[156:159], v69 offset:43008
	ds_read_b128 v[160:163], v70 offset:32768
	ds_read_b128 v[164:167], v70 offset:34816
	ds_read_b128 v[168:171], v71 offset:40960
	ds_read_b128 v[172:175], v71 offset:43008
	s_mov_b64 s[64:65], 0xa000
	s_mov_b32 m0, s38
	s_mov_b64 s[68:69], 0xa400
	v_lshl_add_u64 v[182:183], v[64:65], 0, s[64:65]
	v_lshl_add_u64 v[180:181], v[64:65], 0, s[68:69]
	global_load_lds_dwordx4 v[182:183], off
	s_mov_b32 m0, s37
	v_lshl_add_u64 v[176:177], v[66:67], 0, s[64:65]
	global_load_lds_dwordx4 v[180:181], off
	s_mov_b32 m0, s39
	v_lshl_add_u64 v[178:179], v[66:67], 0, s[68:69]
	global_load_lds_dwordx4 v[176:177], off
	s_mov_b32 m0, s40
	s_nop 0
	global_load_lds_dwordx4 v[178:179], off
	s_waitcnt lgkmcnt(0)
	v_mfma_f32_32x32x16_bf16 v[32:47], v[88:91], v[152:155], v[32:47]
	s_waitcnt vmcnt(8)
	s_waitcnt lgkmcnt(0)
	s_barrier
	v_mfma_f32_32x32x16_bf16 v[48:63], v[88:91], v[156:159], v[48:63]
	v_mfma_f32_32x32x16_bf16 v[0:15], v[92:95], v[152:155], v[0:15]
	v_mfma_f32_32x32x16_bf16 v[16:31], v[92:95], v[156:159], v[16:31]
	v_mfma_f32_32x32x16_bf16 v[32:47], v[160:163], v[168:171], v[32:47]
	v_mfma_f32_32x32x16_bf16 v[48:63], v[160:163], v[172:175], v[48:63]
	v_mfma_f32_32x32x16_bf16 v[0:15], v[164:167], v[168:171], v[0:15]
	v_mfma_f32_32x32x16_bf16 v[16:31], v[164:167], v[172:175], v[16:31]
	ds_read_b128 v[88:91], v68 offset:49152
	ds_read_b128 v[92:95], v68 offset:51200
	ds_read_b128 v[152:155], v69 offset:57344
	ds_read_b128 v[156:159], v69 offset:59392
	ds_read_b128 v[160:163], v70 offset:49152
	ds_read_b128 v[164:167], v70 offset:51200
	ds_read_b128 v[168:171], v71 offset:57344
	ds_read_b128 v[172:175], v71 offset:59392
	s_mov_b64 s[64:65], 0xc000
	s_mov_b32 m0, s34
	s_mov_b64 s[68:69], 0xc400
	v_lshl_add_u64 v[182:183], v[64:65], 0, s[64:65]
	v_lshl_add_u64 v[180:181], v[64:65], 0, s[68:69]
	global_load_lds_dwordx4 v[182:183], off
	s_mov_b32 m0, s30
	v_lshl_add_u64 v[176:177], v[66:67], 0, s[64:65]
	global_load_lds_dwordx4 v[180:181], off
	s_mov_b32 m0, s35
	v_lshl_add_u64 v[178:179], v[66:67], 0, s[68:69]
	global_load_lds_dwordx4 v[176:177], off
	s_mov_b32 m0, s36
	s_nop 0
	global_load_lds_dwordx4 v[178:179], off
	s_waitcnt lgkmcnt(0)
	v_mfma_f32_32x32x16_bf16 v[32:47], v[88:91], v[152:155], v[32:47]
	s_waitcnt vmcnt(8)
	s_waitcnt lgkmcnt(0)
	s_barrier
	v_mfma_f32_32x32x16_bf16 v[48:63], v[88:91], v[156:159], v[48:63]
	v_mfma_f32_32x32x16_bf16 v[0:15], v[92:95], v[152:155], v[0:15]
	v_mfma_f32_32x32x16_bf16 v[16:31], v[92:95], v[156:159], v[16:31]
	v_mfma_f32_32x32x16_bf16 v[32:47], v[160:163], v[168:171], v[32:47]
	v_mfma_f32_32x32x16_bf16 v[48:63], v[160:163], v[172:175], v[48:63]
	v_mfma_f32_32x32x16_bf16 v[0:15], v[164:167], v[168:171], v[0:15]
	v_mfma_f32_32x32x16_bf16 v[16:31], v[164:167], v[172:175], v[16:31]
	ds_read_b128 v[88:91], v68
	ds_read_b128 v[92:95], v68 offset:2048
	ds_read_b128 v[152:155], v69 offset:8192
	ds_read_b128 v[156:159], v69 offset:10240
	ds_read_b128 v[160:163], v70
	ds_read_b128 v[164:167], v70 offset:2048
	ds_read_b128 v[168:171], v71 offset:8192
	ds_read_b128 v[172:175], v71 offset:10240
	s_mov_b64 s[68:69], 0xe000
	s_mov_b32 m0, s22
	s_mov_b64 s[64:65], 0xe400
	v_lshl_add_u64 v[182:183], v[64:65], 0, s[68:69]
	v_lshl_add_u64 v[180:181], v[64:65], 0, s[64:65]
	global_load_lds_dwordx4 v[182:183], off
	s_mov_b32 m0, s1
	v_lshl_add_u64 v[176:177], v[66:67], 0, s[68:69]
	global_load_lds_dwordx4 v[180:181], off
	s_mov_b32 m0, s21
	v_lshl_add_u64 v[178:179], v[66:67], 0, s[64:65]
	global_load_lds_dwordx4 v[176:177], off
	s_mov_b32 m0, s23
	s_nop 0
	global_load_lds_dwordx4 v[178:179], off
	s_waitcnt lgkmcnt(0)
	v_mfma_f32_32x32x16_bf16 v[32:47], v[88:91], v[152:155], v[32:47]
	s_waitcnt vmcnt(8)
	s_waitcnt lgkmcnt(0)
	s_barrier
	v_mfma_f32_32x32x16_bf16 v[48:63], v[88:91], v[156:159], v[48:63]
	v_mfma_f32_32x32x16_bf16 v[0:15], v[92:95], v[152:155], v[0:15]
	v_mfma_f32_32x32x16_bf16 v[16:31], v[92:95], v[156:159], v[16:31]
	v_mfma_f32_32x32x16_bf16 v[32:47], v[160:163], v[168:171], v[32:47]
	v_mfma_f32_32x32x16_bf16 v[48:63], v[160:163], v[172:175], v[48:63]
	v_mfma_f32_32x32x16_bf16 v[0:15], v[164:167], v[168:171], v[0:15]
	v_mfma_f32_32x32x16_bf16 v[16:31], v[164:167], v[172:175], v[16:31]
	ds_read_b128 v[88:91], v68 offset:16384
	ds_read_b128 v[92:95], v68 offset:18432
	ds_read_b128 v[152:155], v69 offset:24576
	ds_read_b128 v[156:159], v69 offset:26624
	ds_read_b128 v[160:163], v70 offset:16384
	ds_read_b128 v[164:167], v70 offset:18432
	ds_read_b128 v[168:171], v71 offset:24576
	ds_read_b128 v[172:175], v71 offset:26624
	s_mov_b64 s[68:69], 0x10000
	s_mov_b32 m0, s43
	s_mov_b64 s[64:65], 0x10400
	v_lshl_add_u64 v[182:183], v[64:65], 0, s[68:69]
	v_lshl_add_u64 v[180:181], v[64:65], 0, s[64:65]
	global_load_lds_dwordx4 v[182:183], off
	s_mov_b32 m0, s41
	v_lshl_add_u64 v[176:177], v[66:67], 0, s[68:69]
	global_load_lds_dwordx4 v[180:181], off
	s_mov_b32 m0, s42
	v_lshl_add_u64 v[178:179], v[66:67], 0, s[64:65]
	global_load_lds_dwordx4 v[176:177], off
	s_mov_b32 m0, s48
	s_nop 0
	global_load_lds_dwordx4 v[178:179], off
	s_waitcnt lgkmcnt(0)
	v_mfma_f32_32x32x16_bf16 v[32:47], v[88:91], v[152:155], v[32:47]
	s_waitcnt vmcnt(8)
	s_waitcnt lgkmcnt(0)
	s_barrier
	v_mfma_f32_32x32x16_bf16 v[48:63], v[88:91], v[156:159], v[48:63]
	v_mfma_f32_32x32x16_bf16 v[0:15], v[92:95], v[152:155], v[0:15]
	v_mfma_f32_32x32x16_bf16 v[16:31], v[92:95], v[156:159], v[16:31]
	v_mfma_f32_32x32x16_bf16 v[32:47], v[160:163], v[168:171], v[32:47]
	v_mfma_f32_32x32x16_bf16 v[48:63], v[160:163], v[172:175], v[48:63]
	v_mfma_f32_32x32x16_bf16 v[0:15], v[164:167], v[168:171], v[0:15]
	v_mfma_f32_32x32x16_bf16 v[16:31], v[164:167], v[172:175], v[16:31]
	ds_read_b128 v[88:91], v68 offset:32768
	ds_read_b128 v[92:95], v68 offset:34816
	ds_read_b128 v[152:155], v69 offset:40960
	ds_read_b128 v[156:159], v69 offset:43008
	ds_read_b128 v[160:163], v70 offset:32768
	ds_read_b128 v[164:167], v70 offset:34816
	ds_read_b128 v[168:171], v71 offset:40960
	ds_read_b128 v[172:175], v71 offset:43008
	s_mov_b64 s[68:69], 0x12000
	s_mov_b32 m0, s38
	s_mov_b64 s[64:65], 0x12400
	v_lshl_add_u64 v[182:183], v[64:65], 0, s[68:69]
	v_lshl_add_u64 v[180:181], v[64:65], 0, s[64:65]
	global_load_lds_dwordx4 v[182:183], off
	s_mov_b32 m0, s37
	v_lshl_add_u64 v[176:177], v[66:67], 0, s[68:69]
	global_load_lds_dwordx4 v[180:181], off
	s_mov_b32 m0, s39
	v_lshl_add_u64 v[178:179], v[66:67], 0, s[64:65]
	global_load_lds_dwordx4 v[176:177], off
	s_mov_b32 m0, s40
	s_nop 0
	global_load_lds_dwordx4 v[178:179], off
	s_waitcnt lgkmcnt(0)
	v_mfma_f32_32x32x16_bf16 v[32:47], v[88:91], v[152:155], v[32:47]
	s_waitcnt vmcnt(8)
	s_waitcnt lgkmcnt(0)
	s_barrier
	v_mfma_f32_32x32x16_bf16 v[48:63], v[88:91], v[156:159], v[48:63]
	v_mfma_f32_32x32x16_bf16 v[0:15], v[92:95], v[152:155], v[0:15]
	v_mfma_f32_32x32x16_bf16 v[16:31], v[92:95], v[156:159], v[16:31]
	v_mfma_f32_32x32x16_bf16 v[32:47], v[160:163], v[168:171], v[32:47]
	v_mfma_f32_32x32x16_bf16 v[48:63], v[160:163], v[172:175], v[48:63]
	v_mfma_f32_32x32x16_bf16 v[0:15], v[164:167], v[168:171], v[0:15]
	v_mfma_f32_32x32x16_bf16 v[16:31], v[164:167], v[172:175], v[16:31]
	ds_read_b128 v[88:91], v68 offset:49152
	ds_read_b128 v[92:95], v68 offset:51200
	ds_read_b128 v[152:155], v69 offset:57344
	ds_read_b128 v[156:159], v69 offset:59392
	ds_read_b128 v[160:163], v70 offset:49152
	ds_read_b128 v[164:167], v70 offset:51200
	ds_read_b128 v[168:171], v71 offset:57344
	ds_read_b128 v[172:175], v71 offset:59392
	s_mov_b64 s[68:69], 0x14000
	s_mov_b32 m0, s34
	s_mov_b64 s[64:65], 0x14400
	v_lshl_add_u64 v[182:183], v[64:65], 0, s[68:69]
	v_lshl_add_u64 v[180:181], v[64:65], 0, s[64:65]
	global_load_lds_dwordx4 v[182:183], off
	s_mov_b32 m0, s30
	v_lshl_add_u64 v[176:177], v[66:67], 0, s[68:69]
	global_load_lds_dwordx4 v[180:181], off
	s_mov_b32 m0, s35
	v_lshl_add_u64 v[178:179], v[66:67], 0, s[64:65]
	global_load_lds_dwordx4 v[176:177], off
	s_mov_b32 m0, s36
	s_nop 0
	global_load_lds_dwordx4 v[178:179], off
	s_waitcnt lgkmcnt(0)
	v_mfma_f32_32x32x16_bf16 v[32:47], v[88:91], v[152:155], v[32:47]
	s_waitcnt vmcnt(8)
	s_waitcnt lgkmcnt(0)
	s_barrier
	v_mfma_f32_32x32x16_bf16 v[48:63], v[88:91], v[156:159], v[48:63]
	v_mfma_f32_32x32x16_bf16 v[0:15], v[92:95], v[152:155], v[0:15]
	v_mfma_f32_32x32x16_bf16 v[16:31], v[92:95], v[156:159], v[16:31]
	v_mfma_f32_32x32x16_bf16 v[32:47], v[160:163], v[168:171], v[32:47]
	v_mfma_f32_32x32x16_bf16 v[48:63], v[160:163], v[172:175], v[48:63]
	v_mfma_f32_32x32x16_bf16 v[0:15], v[164:167], v[168:171], v[0:15]
	v_mfma_f32_32x32x16_bf16 v[16:31], v[164:167], v[172:175], v[16:31]
	ds_read_b128 v[88:91], v68
	ds_read_b128 v[92:95], v68 offset:2048
	ds_read_b128 v[152:155], v69 offset:8192
	ds_read_b128 v[156:159], v69 offset:10240
	ds_read_b128 v[160:163], v70
	ds_read_b128 v[164:167], v70 offset:2048
	ds_read_b128 v[168:171], v71 offset:8192
	ds_read_b128 v[172:175], v71 offset:10240
	s_mov_b64 s[68:69], 0x16000
	s_mov_b32 m0, s22
	s_mov_b64 s[64:65], 0x16400
	v_lshl_add_u64 v[182:183], v[64:65], 0, s[68:69]
	v_lshl_add_u64 v[180:181], v[64:65], 0, s[64:65]
	global_load_lds_dwordx4 v[182:183], off
	s_mov_b32 m0, s1
	v_lshl_add_u64 v[176:177], v[66:67], 0, s[68:69]
	global_load_lds_dwordx4 v[180:181], off
	s_mov_b32 m0, s21
	v_lshl_add_u64 v[178:179], v[66:67], 0, s[64:65]
	global_load_lds_dwordx4 v[176:177], off
	s_mov_b32 m0, s23
	s_nop 0
	global_load_lds_dwordx4 v[178:179], off
	s_waitcnt lgkmcnt(0)
	v_mfma_f32_32x32x16_bf16 v[32:47], v[88:91], v[152:155], v[32:47]
	s_waitcnt vmcnt(8)
	s_waitcnt lgkmcnt(0)
	s_barrier
	v_mfma_f32_32x32x16_bf16 v[48:63], v[88:91], v[156:159], v[48:63]
	v_mfma_f32_32x32x16_bf16 v[0:15], v[92:95], v[152:155], v[0:15]
	v_mfma_f32_32x32x16_bf16 v[16:31], v[92:95], v[156:159], v[16:31]
	v_mfma_f32_32x32x16_bf16 v[32:47], v[160:163], v[168:171], v[32:47]
	v_mfma_f32_32x32x16_bf16 v[48:63], v[160:163], v[172:175], v[48:63]
	v_mfma_f32_32x32x16_bf16 v[0:15], v[164:167], v[168:171], v[0:15]
	v_mfma_f32_32x32x16_bf16 v[16:31], v[164:167], v[172:175], v[16:31]
	ds_read_b128 v[88:91], v68 offset:16384
	ds_read_b128 v[92:95], v68 offset:18432
	ds_read_b128 v[152:155], v69 offset:24576
	ds_read_b128 v[156:159], v69 offset:26624
	ds_read_b128 v[160:163], v70 offset:16384
	ds_read_b128 v[164:167], v70 offset:18432
	ds_read_b128 v[168:171], v71 offset:24576
	ds_read_b128 v[172:175], v71 offset:26624
	s_mov_b64 s[68:69], 0x18000
	s_mov_b32 m0, s43
	s_mov_b64 s[64:65], 0x18400
	v_lshl_add_u64 v[182:183], v[64:65], 0, s[68:69]
	v_lshl_add_u64 v[180:181], v[64:65], 0, s[64:65]
	global_load_lds_dwordx4 v[182:183], off
	s_mov_b32 m0, s41
	v_lshl_add_u64 v[176:177], v[66:67], 0, s[68:69]
	global_load_lds_dwordx4 v[180:181], off
	s_mov_b32 m0, s42
	v_lshl_add_u64 v[178:179], v[66:67], 0, s[64:65]
	global_load_lds_dwordx4 v[176:177], off
	s_mov_b32 m0, s48
	s_nop 0
	global_load_lds_dwordx4 v[178:179], off
	s_waitcnt lgkmcnt(0)
	v_mfma_f32_32x32x16_bf16 v[32:47], v[88:91], v[152:155], v[32:47]
	s_waitcnt vmcnt(8)
	s_waitcnt lgkmcnt(0)
	s_barrier
	v_mfma_f32_32x32x16_bf16 v[48:63], v[88:91], v[156:159], v[48:63]
	v_mfma_f32_32x32x16_bf16 v[0:15], v[92:95], v[152:155], v[0:15]
	v_mfma_f32_32x32x16_bf16 v[16:31], v[92:95], v[156:159], v[16:31]
	v_mfma_f32_32x32x16_bf16 v[32:47], v[160:163], v[168:171], v[32:47]
	v_mfma_f32_32x32x16_bf16 v[48:63], v[160:163], v[172:175], v[48:63]
	v_mfma_f32_32x32x16_bf16 v[0:15], v[164:167], v[168:171], v[0:15]
	v_mfma_f32_32x32x16_bf16 v[16:31], v[164:167], v[172:175], v[16:31]
	ds_read_b128 v[88:91], v68 offset:32768
	ds_read_b128 v[92:95], v68 offset:34816
	ds_read_b128 v[152:155], v69 offset:40960
	ds_read_b128 v[156:159], v69 offset:43008
	ds_read_b128 v[160:163], v70 offset:32768
	ds_read_b128 v[164:167], v70 offset:34816
	ds_read_b128 v[168:171], v71 offset:40960
	ds_read_b128 v[172:175], v71 offset:43008
	s_mov_b64 s[48:49], 0x1a000
	s_mov_b32 m0, s38
	s_mov_b64 s[42:43], 0x1a400
	v_lshl_add_u64 v[182:183], v[64:65], 0, s[48:49]
	v_lshl_add_u64 v[180:181], v[64:65], 0, s[42:43]
	global_load_lds_dwordx4 v[182:183], off
	s_mov_b32 m0, s37
	v_lshl_add_u64 v[176:177], v[66:67], 0, s[48:49]
	global_load_lds_dwordx4 v[180:181], off
	s_mov_b32 m0, s39
	v_lshl_add_u64 v[178:179], v[66:67], 0, s[42:43]
	global_load_lds_dwordx4 v[176:177], off
	s_mov_b32 m0, s40
	s_nop 0
	global_load_lds_dwordx4 v[178:179], off
	s_waitcnt lgkmcnt(0)
	v_mfma_f32_32x32x16_bf16 v[32:47], v[88:91], v[152:155], v[32:47]
	s_waitcnt vmcnt(8)
	s_waitcnt lgkmcnt(0)
	s_barrier
	v_mfma_f32_32x32x16_bf16 v[48:63], v[88:91], v[156:159], v[48:63]
	v_mfma_f32_32x32x16_bf16 v[0:15], v[92:95], v[152:155], v[0:15]
	v_mfma_f32_32x32x16_bf16 v[16:31], v[92:95], v[156:159], v[16:31]
	v_mfma_f32_32x32x16_bf16 v[32:47], v[160:163], v[168:171], v[32:47]
	v_mfma_f32_32x32x16_bf16 v[48:63], v[160:163], v[172:175], v[48:63]
	v_mfma_f32_32x32x16_bf16 v[0:15], v[164:167], v[168:171], v[0:15]
	v_mfma_f32_32x32x16_bf16 v[16:31], v[164:167], v[172:175], v[16:31]
	ds_read_b128 v[88:91], v68 offset:49152
	ds_read_b128 v[92:95], v68 offset:51200
	ds_read_b128 v[152:155], v69 offset:57344
	ds_read_b128 v[156:159], v69 offset:59392
	ds_read_b128 v[160:163], v70 offset:49152
	ds_read_b128 v[164:167], v70 offset:51200
	ds_read_b128 v[168:171], v71 offset:57344
	ds_read_b128 v[172:175], v71 offset:59392
	s_mov_b64 s[40:41], 0x1c000
	s_mov_b32 m0, s34
	s_mov_b64 s[38:39], 0x1c400
	v_lshl_add_u64 v[182:183], v[64:65], 0, s[40:41]
	v_lshl_add_u64 v[180:181], v[64:65], 0, s[38:39]
	global_load_lds_dwordx4 v[182:183], off
	s_mov_b32 m0, s30
	v_lshl_add_u64 v[176:177], v[66:67], 0, s[40:41]
	global_load_lds_dwordx4 v[180:181], off
	s_mov_b32 m0, s35
	v_lshl_add_u64 v[178:179], v[66:67], 0, s[38:39]
	global_load_lds_dwordx4 v[176:177], off
	s_mov_b32 m0, s36
	s_nop 0
	global_load_lds_dwordx4 v[178:179], off
	s_waitcnt lgkmcnt(0)
	v_mfma_f32_32x32x16_bf16 v[32:47], v[88:91], v[152:155], v[32:47]
	s_waitcnt vmcnt(8)
	s_waitcnt lgkmcnt(0)
	s_barrier
	v_mfma_f32_32x32x16_bf16 v[48:63], v[88:91], v[156:159], v[48:63]
	v_mfma_f32_32x32x16_bf16 v[0:15], v[92:95], v[152:155], v[0:15]
	v_mfma_f32_32x32x16_bf16 v[16:31], v[92:95], v[156:159], v[16:31]
	v_mfma_f32_32x32x16_bf16 v[32:47], v[160:163], v[168:171], v[32:47]
	v_mfma_f32_32x32x16_bf16 v[48:63], v[160:163], v[172:175], v[48:63]
	v_mfma_f32_32x32x16_bf16 v[0:15], v[164:167], v[168:171], v[0:15]
	v_mfma_f32_32x32x16_bf16 v[16:31], v[164:167], v[172:175], v[16:31]
	ds_read_b128 v[88:91], v68
	ds_read_b128 v[92:95], v68 offset:2048
	ds_read_b128 v[152:155], v69 offset:8192
	ds_read_b128 v[156:159], v69 offset:10240
	ds_read_b128 v[160:163], v70
	ds_read_b128 v[164:167], v70 offset:2048
	ds_read_b128 v[168:171], v71 offset:8192
	ds_read_b128 v[172:175], v71 offset:10240
	s_mov_b64 s[36:37], 0x1e000
	s_mov_b32 m0, s22
	s_mov_b64 s[34:35], 0x1e400
	v_lshl_add_u64 v[182:183], v[64:65], 0, s[36:37]
	v_lshl_add_u64 v[180:181], v[64:65], 0, s[34:35]
	global_load_lds_dwordx4 v[182:183], off
	s_mov_b32 m0, s1
	v_lshl_add_u64 v[176:177], v[66:67], 0, s[36:37]
	global_load_lds_dwordx4 v[180:181], off
	s_mov_b32 m0, s21
	v_lshl_add_u64 v[178:179], v[66:67], 0, s[34:35]
	global_load_lds_dwordx4 v[176:177], off
	s_mov_b32 m0, s23
	s_nop 0
	global_load_lds_dwordx4 v[178:179], off
	s_waitcnt lgkmcnt(0)
	v_mfma_f32_32x32x16_bf16 v[32:47], v[88:91], v[152:155], v[32:47]
	s_waitcnt vmcnt(8)
	s_waitcnt lgkmcnt(0)
	s_barrier
	v_mfma_f32_32x32x16_bf16 v[48:63], v[88:91], v[156:159], v[48:63]
	v_mfma_f32_32x32x16_bf16 v[0:15], v[92:95], v[152:155], v[0:15]
	v_mfma_f32_32x32x16_bf16 v[16:31], v[92:95], v[156:159], v[16:31]
	v_mfma_f32_32x32x16_bf16 v[32:47], v[160:163], v[168:171], v[32:47]
	v_mfma_f32_32x32x16_bf16 v[48:63], v[160:163], v[172:175], v[48:63]
	v_mfma_f32_32x32x16_bf16 v[0:15], v[164:167], v[168:171], v[0:15]
	v_mfma_f32_32x32x16_bf16 v[16:31], v[164:167], v[172:175], v[16:31]
	ds_read_b128 v[88:91], v68 offset:16384
	ds_read_b128 v[92:95], v68 offset:18432
	ds_read_b128 v[152:155], v69 offset:24576
	ds_read_b128 v[156:159], v69 offset:26624
	ds_read_b128 v[160:163], v70 offset:16384
	ds_read_b128 v[164:167], v70 offset:18432
	ds_read_b128 v[168:171], v71 offset:24576
	ds_read_b128 v[172:175], v71 offset:26624
	s_mov_b64 s[34:35], 0x20000
	v_lshl_add_u64 v[176:177], v[66:67], 0, s[34:35]
	v_lshl_add_u64 v[182:183], v[64:65], 0, s[34:35]
	v_readfirstlane_b32 s34, v101
	s_mov_b64 s[22:23], 0x20400
	s_mov_b32 m0, s34
	v_readfirstlane_b32 s1, v84
	v_lshl_add_u64 v[180:181], v[64:65], 0, s[22:23]
	global_load_lds_dwordx4 v[182:183], off
	s_mov_b32 m0, s1
	v_readfirstlane_b32 s21, v85
	v_lshl_add_u64 v[178:179], v[66:67], 0, s[22:23]
	global_load_lds_dwordx4 v[180:181], off
	s_mov_b32 m0, s21
	v_readfirstlane_b32 s22, v86
	global_load_lds_dwordx4 v[176:177], off
	s_mov_b32 m0, s22
	s_nop 0
	global_load_lds_dwordx4 v[178:179], off
	s_waitcnt lgkmcnt(0)
	v_mfma_f32_32x32x16_bf16 v[32:47], v[88:91], v[152:155], v[32:47]
	s_waitcnt vmcnt(8)
	s_waitcnt lgkmcnt(0)
	s_barrier
	v_mfma_f32_32x32x16_bf16 v[48:63], v[88:91], v[156:159], v[48:63]
	v_mfma_f32_32x32x16_bf16 v[0:15], v[92:95], v[152:155], v[0:15]
	v_mfma_f32_32x32x16_bf16 v[16:31], v[92:95], v[156:159], v[16:31]
	v_mfma_f32_32x32x16_bf16 v[32:47], v[160:163], v[168:171], v[32:47]
	v_mfma_f32_32x32x16_bf16 v[48:63], v[160:163], v[172:175], v[48:63]
	v_mfma_f32_32x32x16_bf16 v[0:15], v[164:167], v[168:171], v[0:15]
	v_mfma_f32_32x32x16_bf16 v[16:31], v[164:167], v[172:175], v[16:31]
	ds_read_b128 v[84:87], v68 offset:32768
	ds_read_b128 v[88:91], v68 offset:34816
	ds_read_b128 v[92:95], v69 offset:40960
	ds_read_b128 v[152:155], v69 offset:43008
	ds_read_b128 v[156:159], v70 offset:32768
	ds_read_b128 v[160:163], v70 offset:34816
	ds_read_b128 v[164:167], v71 offset:40960
	ds_read_b128 v[168:171], v71 offset:43008
	s_mov_b64 s[38:39], 0x22000
	v_lshl_add_u64 v[172:173], v[66:67], 0, s[38:39]
	v_lshl_add_u64 v[178:179], v[64:65], 0, s[38:39]
	v_readfirstlane_b32 s38, v80
	s_mov_b64 s[36:37], 0x22400
	s_mov_b32 m0, s38
	v_readfirstlane_b32 s23, v81
	v_lshl_add_u64 v[176:177], v[64:65], 0, s[36:37]
	global_load_lds_dwordx4 v[178:179], off
	s_mov_b32 m0, s23
	v_readfirstlane_b32 s30, v82
	global_load_lds_dwordx4 v[176:177], off
	s_mov_b32 m0, s30
	v_readfirstlane_b32 s35, v83
	v_lshl_add_u64 v[174:175], v[66:67], 0, s[36:37]
	global_load_lds_dwordx4 v[172:173], off
	s_mov_b32 m0, s35
	s_nop 0
	global_load_lds_dwordx4 v[174:175], off
	s_waitcnt lgkmcnt(0)
	v_mfma_f32_32x32x16_bf16 v[32:47], v[84:87], v[92:95], v[32:47]
	s_waitcnt vmcnt(8)
	s_waitcnt lgkmcnt(0)
	s_barrier
	v_mfma_f32_32x32x16_bf16 v[48:63], v[84:87], v[152:155], v[48:63]
	v_mfma_f32_32x32x16_bf16 v[0:15], v[88:91], v[92:95], v[0:15]
	v_mfma_f32_32x32x16_bf16 v[16:31], v[88:91], v[152:155], v[16:31]
	v_mfma_f32_32x32x16_bf16 v[32:47], v[156:159], v[164:167], v[32:47]
	v_mfma_f32_32x32x16_bf16 v[48:63], v[156:159], v[168:171], v[48:63]
	v_mfma_f32_32x32x16_bf16 v[0:15], v[160:163], v[164:167], v[0:15]
	v_mfma_f32_32x32x16_bf16 v[16:31], v[160:163], v[168:171], v[16:31]
	ds_read_b128 v[80:83], v68 offset:49152
	ds_read_b128 v[84:87], v68 offset:51200
	ds_read_b128 v[88:91], v69 offset:57344
	ds_read_b128 v[92:95], v69 offset:59392
	ds_read_b128 v[152:155], v70 offset:49152
	ds_read_b128 v[156:159], v70 offset:51200
	ds_read_b128 v[160:163], v71 offset:57344
	ds_read_b128 v[164:167], v71 offset:59392
	s_mov_b64 s[40:41], 0x24000
	s_mov_b64 s[36:37], 0x24400
	v_readfirstlane_b32 s42, v76
	v_lshl_add_u64 v[170:171], v[66:67], 0, s[36:37]
	v_lshl_add_u64 v[172:173], v[64:65], 0, s[36:37]
	v_lshl_add_u64 v[174:175], v[64:65], 0, s[40:41]
	s_mov_b32 m0, s42
	v_readfirstlane_b32 s36, v77
	global_load_lds_dwordx4 v[174:175], off
	s_mov_b32 m0, s36
	v_readfirstlane_b32 s37, v78
	v_lshl_add_u64 v[168:169], v[66:67], 0, s[40:41]
	global_load_lds_dwordx4 v[172:173], off
	s_mov_b32 m0, s37
	v_readfirstlane_b32 s39, v79
	global_load_lds_dwordx4 v[168:169], off
	s_mov_b32 m0, s39
	s_nop 0
	global_load_lds_dwordx4 v[170:171], off
	s_waitcnt lgkmcnt(0)
	v_mfma_f32_32x32x16_bf16 v[32:47], v[80:83], v[88:91], v[32:47]
	s_waitcnt vmcnt(8)
	s_waitcnt lgkmcnt(0)
	s_barrier
	v_mfma_f32_32x32x16_bf16 v[48:63], v[80:83], v[92:95], v[48:63]
	v_mfma_f32_32x32x16_bf16 v[0:15], v[84:87], v[88:91], v[0:15]
	v_mfma_f32_32x32x16_bf16 v[16:31], v[84:87], v[92:95], v[16:31]
	v_mfma_f32_32x32x16_bf16 v[32:47], v[152:155], v[160:163], v[32:47]
	v_mfma_f32_32x32x16_bf16 v[48:63], v[152:155], v[164:167], v[48:63]
	v_mfma_f32_32x32x16_bf16 v[0:15], v[156:159], v[160:163], v[0:15]
	v_mfma_f32_32x32x16_bf16 v[16:31], v[156:159], v[164:167], v[16:31]
	ds_read_b128 v[76:79], v68
	ds_read_b128 v[80:83], v68 offset:2048
	ds_read_b128 v[84:87], v69 offset:8192
	ds_read_b128 v[88:91], v69 offset:10240
	ds_read_b128 v[92:95], v70
	ds_read_b128 v[152:155], v70 offset:2048
	ds_read_b128 v[156:159], v71 offset:8192
	ds_read_b128 v[160:163], v71 offset:10240
	s_mov_b64 s[48:49], 0x26000
	v_lshl_add_u64 v[164:165], v[66:67], 0, s[48:49]
	s_mov_b64 s[40:41], 0x26400
	v_lshl_add_u64 v[170:171], v[64:65], 0, s[48:49]
	v_readfirstlane_b32 s48, v72
	v_lshl_add_u64 v[166:167], v[66:67], 0, s[40:41]
	v_lshl_add_u64 v[168:169], v[64:65], 0, s[40:41]
	s_mov_b32 m0, s48
	v_readfirstlane_b32 s40, v73
	global_load_lds_dwordx4 v[170:171], off
	s_mov_b32 m0, s40
	v_readfirstlane_b32 s41, v74
	global_load_lds_dwordx4 v[168:169], off
	s_mov_b32 m0, s41
	v_readfirstlane_b32 s43, v75
	global_load_lds_dwordx4 v[164:165], off
	s_mov_b32 m0, s43
	s_nop 0
	global_load_lds_dwordx4 v[166:167], off
	s_waitcnt lgkmcnt(0)
	v_mfma_f32_32x32x16_bf16 v[32:47], v[76:79], v[84:87], v[32:47]
	s_waitcnt vmcnt(8)
	s_waitcnt lgkmcnt(0)
	s_barrier
	v_mfma_f32_32x32x16_bf16 v[48:63], v[76:79], v[88:91], v[48:63]
	v_mfma_f32_32x32x16_bf16 v[0:15], v[80:83], v[84:87], v[0:15]
	v_mfma_f32_32x32x16_bf16 v[16:31], v[80:83], v[88:91], v[16:31]
	v_mfma_f32_32x32x16_bf16 v[32:47], v[92:95], v[156:159], v[32:47]
	v_mfma_f32_32x32x16_bf16 v[48:63], v[92:95], v[160:163], v[48:63]
	v_mfma_f32_32x32x16_bf16 v[0:15], v[152:155], v[156:159], v[0:15]
	v_mfma_f32_32x32x16_bf16 v[16:31], v[152:155], v[160:163], v[16:31]
	ds_read_b128 v[72:75], v68 offset:16384
	ds_read_b128 v[76:79], v68 offset:18432
	ds_read_b128 v[80:83], v69 offset:24576
	ds_read_b128 v[84:87], v69 offset:26624
	ds_read_b128 v[88:91], v70 offset:16384
	ds_read_b128 v[92:95], v70 offset:18432
	ds_read_b128 v[152:155], v71 offset:24576
	ds_read_b128 v[156:159], v71 offset:26624
	s_mov_b64 s[64:65], 0x28000
	s_mov_b32 m0, s34
	s_mov_b64 s[68:69], 0x28400
	v_lshl_add_u64 v[166:167], v[64:65], 0, s[64:65]
	v_lshl_add_u64 v[164:165], v[64:65], 0, s[68:69]
	global_load_lds_dwordx4 v[166:167], off
	s_mov_b32 m0, s1
	v_lshl_add_u64 v[160:161], v[66:67], 0, s[64:65]
	global_load_lds_dwordx4 v[164:165], off
	s_mov_b32 m0, s21
	v_lshl_add_u64 v[162:163], v[66:67], 0, s[68:69]
	global_load_lds_dwordx4 v[160:161], off
	s_mov_b32 m0, s22
	s_nop 0
	global_load_lds_dwordx4 v[162:163], off
	s_waitcnt lgkmcnt(0)
	v_mfma_f32_32x32x16_bf16 v[32:47], v[72:75], v[80:83], v[32:47]
	s_waitcnt vmcnt(8)
	s_waitcnt lgkmcnt(0)
	s_barrier
	v_mfma_f32_32x32x16_bf16 v[48:63], v[72:75], v[84:87], v[48:63]
	v_mfma_f32_32x32x16_bf16 v[0:15], v[76:79], v[80:83], v[0:15]
	v_mfma_f32_32x32x16_bf16 v[16:31], v[76:79], v[84:87], v[16:31]
	v_mfma_f32_32x32x16_bf16 v[32:47], v[88:91], v[152:155], v[32:47]
	v_mfma_f32_32x32x16_bf16 v[48:63], v[88:91], v[156:159], v[48:63]
	v_mfma_f32_32x32x16_bf16 v[0:15], v[92:95], v[152:155], v[0:15]
	v_mfma_f32_32x32x16_bf16 v[16:31], v[92:95], v[156:159], v[16:31]
	ds_read_b128 v[72:75], v68 offset:32768
	ds_read_b128 v[76:79], v68 offset:34816
	ds_read_b128 v[80:83], v69 offset:40960
	ds_read_b128 v[84:87], v69 offset:43008
	ds_read_b128 v[88:91], v70 offset:32768
	ds_read_b128 v[92:95], v70 offset:34816
	ds_read_b128 v[152:155], v71 offset:40960
	ds_read_b128 v[156:159], v71 offset:43008
	s_mov_b64 s[64:65], 0x2a000
	s_mov_b32 m0, s38
	s_mov_b64 s[68:69], 0x2a400
	v_lshl_add_u64 v[166:167], v[64:65], 0, s[64:65]
	v_lshl_add_u64 v[164:165], v[64:65], 0, s[68:69]
	global_load_lds_dwordx4 v[166:167], off
	s_mov_b32 m0, s23
	v_lshl_add_u64 v[160:161], v[66:67], 0, s[64:65]
	global_load_lds_dwordx4 v[164:165], off
	s_mov_b32 m0, s30
	v_lshl_add_u64 v[162:163], v[66:67], 0, s[68:69]
	global_load_lds_dwordx4 v[160:161], off
	s_mov_b32 m0, s35
	s_nop 0
	global_load_lds_dwordx4 v[162:163], off
	s_waitcnt lgkmcnt(0)
	v_mfma_f32_32x32x16_bf16 v[32:47], v[72:75], v[80:83], v[32:47]
	s_waitcnt vmcnt(8)
	s_waitcnt lgkmcnt(0)
	s_barrier
	v_mfma_f32_32x32x16_bf16 v[48:63], v[72:75], v[84:87], v[48:63]
	v_mfma_f32_32x32x16_bf16 v[0:15], v[76:79], v[80:83], v[0:15]
	v_mfma_f32_32x32x16_bf16 v[16:31], v[76:79], v[84:87], v[16:31]
	v_mfma_f32_32x32x16_bf16 v[32:47], v[88:91], v[152:155], v[32:47]
	v_mfma_f32_32x32x16_bf16 v[48:63], v[88:91], v[156:159], v[48:63]
	v_mfma_f32_32x32x16_bf16 v[0:15], v[92:95], v[152:155], v[0:15]
	v_mfma_f32_32x32x16_bf16 v[16:31], v[92:95], v[156:159], v[16:31]
	ds_read_b128 v[72:75], v68 offset:49152
	ds_read_b128 v[76:79], v68 offset:51200
	ds_read_b128 v[80:83], v69 offset:57344
	ds_read_b128 v[84:87], v69 offset:59392
	ds_read_b128 v[88:91], v70 offset:49152
	ds_read_b128 v[92:95], v70 offset:51200
	ds_read_b128 v[152:155], v71 offset:57344
	ds_read_b128 v[156:159], v71 offset:59392
	s_mov_b64 s[64:65], 0x2c000
	s_mov_b32 m0, s42
	s_mov_b64 s[68:69], 0x2c400
	v_lshl_add_u64 v[166:167], v[64:65], 0, s[64:65]
	v_lshl_add_u64 v[164:165], v[64:65], 0, s[68:69]
	global_load_lds_dwordx4 v[166:167], off
	s_mov_b32 m0, s36
	v_lshl_add_u64 v[160:161], v[66:67], 0, s[64:65]
	global_load_lds_dwordx4 v[164:165], off
	s_mov_b32 m0, s37
	v_lshl_add_u64 v[162:163], v[66:67], 0, s[68:69]
	global_load_lds_dwordx4 v[160:161], off
	s_mov_b32 m0, s39
	s_nop 0
	global_load_lds_dwordx4 v[162:163], off
	s_waitcnt lgkmcnt(0)
	v_mfma_f32_32x32x16_bf16 v[32:47], v[72:75], v[80:83], v[32:47]
	s_waitcnt vmcnt(8)
	s_waitcnt lgkmcnt(0)
	s_barrier
	v_mfma_f32_32x32x16_bf16 v[48:63], v[72:75], v[84:87], v[48:63]
	v_mfma_f32_32x32x16_bf16 v[0:15], v[76:79], v[80:83], v[0:15]
	v_mfma_f32_32x32x16_bf16 v[16:31], v[76:79], v[84:87], v[16:31]
	v_mfma_f32_32x32x16_bf16 v[32:47], v[88:91], v[152:155], v[32:47]
	v_mfma_f32_32x32x16_bf16 v[48:63], v[88:91], v[156:159], v[48:63]
	v_mfma_f32_32x32x16_bf16 v[0:15], v[92:95], v[152:155], v[0:15]
	v_mfma_f32_32x32x16_bf16 v[16:31], v[92:95], v[156:159], v[16:31]
	ds_read_b128 v[72:75], v68
	ds_read_b128 v[76:79], v68 offset:2048
	ds_read_b128 v[80:83], v69 offset:8192
	ds_read_b128 v[84:87], v69 offset:10240
	ds_read_b128 v[88:91], v70
	ds_read_b128 v[92:95], v70 offset:2048
	ds_read_b128 v[152:155], v71 offset:8192
	ds_read_b128 v[156:159], v71 offset:10240
	s_mov_b64 s[64:65], 0x2e000
	s_mov_b32 m0, s48
	s_mov_b64 s[68:69], 0x2e400
	v_lshl_add_u64 v[166:167], v[64:65], 0, s[64:65]
	v_lshl_add_u64 v[164:165], v[64:65], 0, s[68:69]
	global_load_lds_dwordx4 v[166:167], off
	s_mov_b32 m0, s40
	v_lshl_add_u64 v[160:161], v[66:67], 0, s[64:65]
	global_load_lds_dwordx4 v[164:165], off
	s_mov_b32 m0, s41
	v_lshl_add_u64 v[162:163], v[66:67], 0, s[68:69]
	global_load_lds_dwordx4 v[160:161], off
	s_mov_b32 m0, s43
	s_nop 0
	global_load_lds_dwordx4 v[162:163], off
	s_waitcnt lgkmcnt(0)
	v_mfma_f32_32x32x16_bf16 v[32:47], v[72:75], v[80:83], v[32:47]
	s_waitcnt vmcnt(8)
	s_waitcnt lgkmcnt(0)
	s_barrier
	v_mfma_f32_32x32x16_bf16 v[48:63], v[72:75], v[84:87], v[48:63]
	v_mfma_f32_32x32x16_bf16 v[0:15], v[76:79], v[80:83], v[0:15]
	v_mfma_f32_32x32x16_bf16 v[16:31], v[76:79], v[84:87], v[16:31]
	v_mfma_f32_32x32x16_bf16 v[32:47], v[88:91], v[152:155], v[32:47]
	v_mfma_f32_32x32x16_bf16 v[48:63], v[88:91], v[156:159], v[48:63]
	v_mfma_f32_32x32x16_bf16 v[0:15], v[92:95], v[152:155], v[0:15]
	v_mfma_f32_32x32x16_bf16 v[16:31], v[92:95], v[156:159], v[16:31]
	ds_read_b128 v[72:75], v68 offset:16384
	ds_read_b128 v[76:79], v68 offset:18432
	ds_read_b128 v[80:83], v69 offset:24576
	ds_read_b128 v[84:87], v69 offset:26624
	ds_read_b128 v[88:91], v70 offset:16384
	ds_read_b128 v[92:95], v70 offset:18432
	ds_read_b128 v[152:155], v71 offset:24576
	ds_read_b128 v[156:159], v71 offset:26624
	s_mov_b64 s[64:65], 0x30000
	s_mov_b32 m0, s34
	s_mov_b64 s[68:69], 0x30400
	v_lshl_add_u64 v[166:167], v[64:65], 0, s[64:65]
	v_lshl_add_u64 v[164:165], v[64:65], 0, s[68:69]
	global_load_lds_dwordx4 v[166:167], off
	s_mov_b32 m0, s1
	v_lshl_add_u64 v[160:161], v[66:67], 0, s[64:65]
	global_load_lds_dwordx4 v[164:165], off
	s_mov_b32 m0, s21
	v_lshl_add_u64 v[162:163], v[66:67], 0, s[68:69]
	global_load_lds_dwordx4 v[160:161], off
	s_mov_b32 m0, s22
	s_nop 0
	global_load_lds_dwordx4 v[162:163], off
	s_waitcnt lgkmcnt(0)
	v_mfma_f32_32x32x16_bf16 v[32:47], v[72:75], v[80:83], v[32:47]
	s_waitcnt vmcnt(8)
	s_waitcnt lgkmcnt(0)
	s_barrier
	v_mfma_f32_32x32x16_bf16 v[48:63], v[72:75], v[84:87], v[48:63]
	v_mfma_f32_32x32x16_bf16 v[0:15], v[76:79], v[80:83], v[0:15]
	v_mfma_f32_32x32x16_bf16 v[16:31], v[76:79], v[84:87], v[16:31]
	v_mfma_f32_32x32x16_bf16 v[32:47], v[88:91], v[152:155], v[32:47]
	v_mfma_f32_32x32x16_bf16 v[48:63], v[88:91], v[156:159], v[48:63]
	v_mfma_f32_32x32x16_bf16 v[0:15], v[92:95], v[152:155], v[0:15]
	v_mfma_f32_32x32x16_bf16 v[16:31], v[92:95], v[156:159], v[16:31]
	ds_read_b128 v[72:75], v68 offset:32768
	ds_read_b128 v[76:79], v68 offset:34816
	ds_read_b128 v[80:83], v69 offset:40960
	ds_read_b128 v[84:87], v69 offset:43008
	ds_read_b128 v[88:91], v70 offset:32768
	ds_read_b128 v[92:95], v70 offset:34816
	ds_read_b128 v[152:155], v71 offset:40960
	ds_read_b128 v[156:159], v71 offset:43008
	s_mov_b64 s[64:65], 0x32000
	s_mov_b32 m0, s38
	s_mov_b64 s[68:69], 0x32400
	v_lshl_add_u64 v[166:167], v[64:65], 0, s[64:65]
	v_lshl_add_u64 v[164:165], v[64:65], 0, s[68:69]
	global_load_lds_dwordx4 v[166:167], off
	s_mov_b32 m0, s23
	v_lshl_add_u64 v[160:161], v[66:67], 0, s[64:65]
	global_load_lds_dwordx4 v[164:165], off
	s_mov_b32 m0, s30
	v_lshl_add_u64 v[162:163], v[66:67], 0, s[68:69]
	global_load_lds_dwordx4 v[160:161], off
	s_mov_b32 m0, s35
	s_nop 0
	global_load_lds_dwordx4 v[162:163], off
	s_waitcnt lgkmcnt(0)
	v_mfma_f32_32x32x16_bf16 v[32:47], v[72:75], v[80:83], v[32:47]
	s_waitcnt vmcnt(8)
	s_waitcnt lgkmcnt(0)
	s_barrier
	v_mfma_f32_32x32x16_bf16 v[48:63], v[72:75], v[84:87], v[48:63]
	v_mfma_f32_32x32x16_bf16 v[0:15], v[76:79], v[80:83], v[0:15]
	v_mfma_f32_32x32x16_bf16 v[16:31], v[76:79], v[84:87], v[16:31]
	v_mfma_f32_32x32x16_bf16 v[32:47], v[88:91], v[152:155], v[32:47]
	v_mfma_f32_32x32x16_bf16 v[48:63], v[88:91], v[156:159], v[48:63]
	v_mfma_f32_32x32x16_bf16 v[0:15], v[92:95], v[152:155], v[0:15]
	v_mfma_f32_32x32x16_bf16 v[16:31], v[92:95], v[156:159], v[16:31]
	ds_read_b128 v[72:75], v68 offset:49152
	ds_read_b128 v[76:79], v68 offset:51200
	ds_read_b128 v[80:83], v69 offset:57344
	ds_read_b128 v[84:87], v69 offset:59392
	ds_read_b128 v[88:91], v70 offset:49152
	ds_read_b128 v[92:95], v70 offset:51200
	ds_read_b128 v[152:155], v71 offset:57344
	ds_read_b128 v[156:159], v71 offset:59392
	s_mov_b64 s[64:65], 0x34000
	s_mov_b32 m0, s42
	s_mov_b64 s[68:69], 0x34400
	v_lshl_add_u64 v[166:167], v[64:65], 0, s[64:65]
	v_lshl_add_u64 v[164:165], v[64:65], 0, s[68:69]
	global_load_lds_dwordx4 v[166:167], off
	s_mov_b32 m0, s36
	v_lshl_add_u64 v[160:161], v[66:67], 0, s[64:65]
	global_load_lds_dwordx4 v[164:165], off
	s_mov_b32 m0, s37
	v_lshl_add_u64 v[162:163], v[66:67], 0, s[68:69]
	global_load_lds_dwordx4 v[160:161], off
	s_mov_b32 m0, s39
	s_nop 0
	global_load_lds_dwordx4 v[162:163], off
	s_waitcnt lgkmcnt(0)
	v_mfma_f32_32x32x16_bf16 v[32:47], v[72:75], v[80:83], v[32:47]
	s_waitcnt vmcnt(8)
	s_waitcnt lgkmcnt(0)
	s_barrier
	v_mfma_f32_32x32x16_bf16 v[48:63], v[72:75], v[84:87], v[48:63]
	v_mfma_f32_32x32x16_bf16 v[0:15], v[76:79], v[80:83], v[0:15]
	v_mfma_f32_32x32x16_bf16 v[16:31], v[76:79], v[84:87], v[16:31]
	v_mfma_f32_32x32x16_bf16 v[32:47], v[88:91], v[152:155], v[32:47]
	v_mfma_f32_32x32x16_bf16 v[48:63], v[88:91], v[156:159], v[48:63]
	v_mfma_f32_32x32x16_bf16 v[0:15], v[92:95], v[152:155], v[0:15]
	v_mfma_f32_32x32x16_bf16 v[16:31], v[92:95], v[156:159], v[16:31]
	ds_read_b128 v[72:75], v68
	ds_read_b128 v[76:79], v68 offset:2048
	ds_read_b128 v[80:83], v69 offset:8192
	ds_read_b128 v[84:87], v69 offset:10240
	ds_read_b128 v[88:91], v70
	ds_read_b128 v[92:95], v70 offset:2048
	ds_read_b128 v[152:155], v71 offset:8192
	ds_read_b128 v[156:159], v71 offset:10240
	s_mov_b64 s[64:65], 0x36000
	s_mov_b32 m0, s48
	s_mov_b64 s[68:69], 0x36400
	v_lshl_add_u64 v[166:167], v[64:65], 0, s[64:65]
	v_lshl_add_u64 v[164:165], v[64:65], 0, s[68:69]
	global_load_lds_dwordx4 v[166:167], off
	s_mov_b32 m0, s40
	v_lshl_add_u64 v[160:161], v[66:67], 0, s[64:65]
	global_load_lds_dwordx4 v[164:165], off
	s_mov_b32 m0, s41
	v_lshl_add_u64 v[162:163], v[66:67], 0, s[68:69]
	global_load_lds_dwordx4 v[160:161], off
	s_mov_b32 m0, s43
	s_nop 0
	global_load_lds_dwordx4 v[162:163], off
	s_waitcnt lgkmcnt(0)
	v_mfma_f32_32x32x16_bf16 v[32:47], v[72:75], v[80:83], v[32:47]
	s_waitcnt vmcnt(8)
	s_waitcnt lgkmcnt(0)
	s_barrier
	v_mfma_f32_32x32x16_bf16 v[48:63], v[72:75], v[84:87], v[48:63]
	v_mfma_f32_32x32x16_bf16 v[0:15], v[76:79], v[80:83], v[0:15]
	v_mfma_f32_32x32x16_bf16 v[16:31], v[76:79], v[84:87], v[16:31]
	v_mfma_f32_32x32x16_bf16 v[32:47], v[88:91], v[152:155], v[32:47]
	v_mfma_f32_32x32x16_bf16 v[48:63], v[88:91], v[156:159], v[48:63]
	v_mfma_f32_32x32x16_bf16 v[0:15], v[92:95], v[152:155], v[0:15]
	v_mfma_f32_32x32x16_bf16 v[16:31], v[92:95], v[156:159], v[16:31]
	ds_read_b128 v[72:75], v68 offset:16384
	ds_read_b128 v[76:79], v68 offset:18432
	ds_read_b128 v[80:83], v69 offset:24576
	ds_read_b128 v[84:87], v69 offset:26624
	ds_read_b128 v[88:91], v70 offset:16384
	ds_read_b128 v[92:95], v70 offset:18432
	ds_read_b128 v[152:155], v71 offset:24576
	ds_read_b128 v[156:159], v71 offset:26624
	s_mov_b64 s[64:65], 0x38000
	s_mov_b32 m0, s34
	s_mov_b64 s[68:69], 0x38400
	v_lshl_add_u64 v[166:167], v[64:65], 0, s[64:65]
	v_lshl_add_u64 v[164:165], v[64:65], 0, s[68:69]
	global_load_lds_dwordx4 v[166:167], off
	s_mov_b32 m0, s1
	v_lshl_add_u64 v[160:161], v[66:67], 0, s[64:65]
	global_load_lds_dwordx4 v[164:165], off
	s_mov_b32 m0, s21
	v_lshl_add_u64 v[162:163], v[66:67], 0, s[68:69]
	global_load_lds_dwordx4 v[160:161], off
	s_mov_b32 m0, s22
	s_nop 0
	global_load_lds_dwordx4 v[162:163], off
	s_waitcnt lgkmcnt(0)
	v_mfma_f32_32x32x16_bf16 v[32:47], v[72:75], v[80:83], v[32:47]
	s_waitcnt vmcnt(8)
	s_waitcnt lgkmcnt(0)
	s_barrier
	v_mfma_f32_32x32x16_bf16 v[48:63], v[72:75], v[84:87], v[48:63]
	v_mfma_f32_32x32x16_bf16 v[0:15], v[76:79], v[80:83], v[0:15]
	v_mfma_f32_32x32x16_bf16 v[16:31], v[76:79], v[84:87], v[16:31]
	v_mfma_f32_32x32x16_bf16 v[32:47], v[88:91], v[152:155], v[32:47]
	v_mfma_f32_32x32x16_bf16 v[48:63], v[88:91], v[156:159], v[48:63]
	v_mfma_f32_32x32x16_bf16 v[0:15], v[92:95], v[152:155], v[0:15]
	v_mfma_f32_32x32x16_bf16 v[16:31], v[92:95], v[156:159], v[16:31]
	ds_read_b128 v[72:75], v68 offset:32768
	ds_read_b128 v[76:79], v68 offset:34816
	ds_read_b128 v[80:83], v69 offset:40960
	ds_read_b128 v[84:87], v69 offset:43008
	ds_read_b128 v[88:91], v70 offset:32768
	ds_read_b128 v[92:95], v70 offset:34816
	ds_read_b128 v[152:155], v71 offset:40960
	ds_read_b128 v[156:159], v71 offset:43008
	s_mov_b64 s[64:65], 0x3a000
	s_mov_b32 m0, s38
	s_mov_b64 s[68:69], 0x3a400
	v_lshl_add_u64 v[166:167], v[64:65], 0, s[64:65]
	v_lshl_add_u64 v[164:165], v[64:65], 0, s[68:69]
	global_load_lds_dwordx4 v[166:167], off
	s_mov_b32 m0, s23
	v_lshl_add_u64 v[160:161], v[66:67], 0, s[64:65]
	global_load_lds_dwordx4 v[164:165], off
	s_mov_b32 m0, s30
	v_lshl_add_u64 v[162:163], v[66:67], 0, s[68:69]
	global_load_lds_dwordx4 v[160:161], off
	s_mov_b32 m0, s35
	s_nop 0
	global_load_lds_dwordx4 v[162:163], off
	s_waitcnt lgkmcnt(0)
	v_mfma_f32_32x32x16_bf16 v[32:47], v[72:75], v[80:83], v[32:47]
	s_waitcnt vmcnt(8)
	s_waitcnt lgkmcnt(0)
	s_barrier
	v_mfma_f32_32x32x16_bf16 v[48:63], v[72:75], v[84:87], v[48:63]
	v_mfma_f32_32x32x16_bf16 v[0:15], v[76:79], v[80:83], v[0:15]
	v_mfma_f32_32x32x16_bf16 v[16:31], v[76:79], v[84:87], v[16:31]
	v_mfma_f32_32x32x16_bf16 v[32:47], v[88:91], v[152:155], v[32:47]
	v_mfma_f32_32x32x16_bf16 v[48:63], v[88:91], v[156:159], v[48:63]
	v_mfma_f32_32x32x16_bf16 v[0:15], v[92:95], v[152:155], v[0:15]
	v_mfma_f32_32x32x16_bf16 v[16:31], v[92:95], v[156:159], v[16:31]
	ds_read_b128 v[72:75], v68 offset:49152
	ds_read_b128 v[76:79], v68 offset:51200
	ds_read_b128 v[80:83], v69 offset:57344
	ds_read_b128 v[84:87], v69 offset:59392
	ds_read_b128 v[88:91], v70 offset:49152
	ds_read_b128 v[92:95], v70 offset:51200
	ds_read_b128 v[152:155], v71 offset:57344
	ds_read_b128 v[156:159], v71 offset:59392
	s_mov_b64 s[22:23], 0x3c000
	s_mov_b32 m0, s42
	s_mov_b64 s[34:35], 0x3c400
	v_lshl_add_u64 v[166:167], v[64:65], 0, s[22:23]
	v_lshl_add_u64 v[164:165], v[64:65], 0, s[34:35]
	global_load_lds_dwordx4 v[166:167], off
	s_mov_b32 m0, s36
	v_lshl_add_u64 v[160:161], v[66:67], 0, s[22:23]
	global_load_lds_dwordx4 v[164:165], off
	s_mov_b32 m0, s37
	v_lshl_add_u64 v[162:163], v[66:67], 0, s[34:35]
	global_load_lds_dwordx4 v[160:161], off
	s_mov_b32 m0, s39
	s_nop 0
	global_load_lds_dwordx4 v[162:163], off
	s_waitcnt lgkmcnt(0)
	v_mfma_f32_32x32x16_bf16 v[32:47], v[72:75], v[80:83], v[32:47]
	s_waitcnt vmcnt(8)
	s_waitcnt lgkmcnt(0)
	s_barrier
	v_mfma_f32_32x32x16_bf16 v[48:63], v[72:75], v[84:87], v[48:63]
	v_mfma_f32_32x32x16_bf16 v[0:15], v[76:79], v[80:83], v[0:15]
	v_mfma_f32_32x32x16_bf16 v[16:31], v[76:79], v[84:87], v[16:31]
	v_mfma_f32_32x32x16_bf16 v[32:47], v[88:91], v[152:155], v[32:47]
	v_mfma_f32_32x32x16_bf16 v[48:63], v[88:91], v[156:159], v[48:63]
	v_mfma_f32_32x32x16_bf16 v[0:15], v[92:95], v[152:155], v[0:15]
	v_mfma_f32_32x32x16_bf16 v[16:31], v[92:95], v[156:159], v[16:31]
	ds_read_b128 v[72:75], v68
	ds_read_b128 v[76:79], v68 offset:2048
	ds_read_b128 v[80:83], v69 offset:8192
	ds_read_b128 v[84:87], v69 offset:10240
	ds_read_b128 v[88:91], v70
	ds_read_b128 v[92:95], v70 offset:2048
	ds_read_b128 v[152:155], v71 offset:8192
	ds_read_b128 v[156:159], v71 offset:10240
	s_mov_b64 s[22:23], 0x3e000
	s_mov_b64 s[34:35], 0x3e400
	s_mov_b32 m0, s48
	v_lshl_add_u64 v[162:163], v[64:65], 0, s[34:35]
	v_lshl_add_u64 v[64:65], v[64:65], 0, s[22:23]
	global_load_lds_dwordx4 v[64:65], off
	s_mov_b32 m0, s40
	v_lshl_add_u64 v[160:161], v[66:67], 0, s[22:23]
	global_load_lds_dwordx4 v[162:163], off
	s_mov_b32 m0, s41
	v_lshl_add_u64 v[66:67], v[66:67], 0, s[34:35]
	global_load_lds_dwordx4 v[160:161], off
	s_mov_b32 m0, s43
	s_nop 0
	global_load_lds_dwordx4 v[66:67], off
	s_waitcnt lgkmcnt(0)
	v_mfma_f32_32x32x16_bf16 v[32:47], v[72:75], v[80:83], v[32:47]
	s_waitcnt vmcnt(8)
	s_waitcnt lgkmcnt(0)
	s_barrier
	v_mfma_f32_32x32x16_bf16 v[48:63], v[72:75], v[84:87], v[48:63]
	v_mfma_f32_32x32x16_bf16 v[0:15], v[76:79], v[80:83], v[0:15]
	v_mfma_f32_32x32x16_bf16 v[16:31], v[76:79], v[84:87], v[16:31]
	v_mfma_f32_32x32x16_bf16 v[32:47], v[88:91], v[152:155], v[32:47]
	v_mfma_f32_32x32x16_bf16 v[48:63], v[88:91], v[156:159], v[48:63]
	v_mfma_f32_32x32x16_bf16 v[0:15], v[92:95], v[152:155], v[0:15]
	v_mfma_f32_32x32x16_bf16 v[16:31], v[92:95], v[156:159], v[16:31]
	ds_read_b128 v[64:67], v68 offset:16384
	ds_read_b128 v[72:75], v68 offset:18432
	ds_read_b128 v[76:79], v69 offset:24576
	ds_read_b128 v[80:83], v69 offset:26624
	ds_read_b128 v[84:87], v70 offset:16384
	ds_read_b128 v[88:91], v70 offset:18432
	ds_read_b128 v[92:95], v71 offset:24576
	ds_read_b128 v[152:155], v71 offset:26624
	s_waitcnt lgkmcnt(0)
	v_mfma_f32_32x32x16_bf16 v[32:47], v[64:67], v[76:79], v[32:47]
	s_waitcnt vmcnt(4)
	s_waitcnt lgkmcnt(0)
	s_barrier
	v_mfma_f32_32x32x16_bf16 v[48:63], v[64:67], v[80:83], v[48:63]
	v_mfma_f32_32x32x16_bf16 v[0:15], v[72:75], v[76:79], v[0:15]
	v_mfma_f32_32x32x16_bf16 v[16:31], v[72:75], v[80:83], v[16:31]
	v_mfma_f32_32x32x16_bf16 v[32:47], v[84:87], v[92:95], v[32:47]
	v_mfma_f32_32x32x16_bf16 v[48:63], v[84:87], v[152:155], v[48:63]
	v_mfma_f32_32x32x16_bf16 v[0:15], v[88:91], v[92:95], v[0:15]
	v_mfma_f32_32x32x16_bf16 v[16:31], v[88:91], v[152:155], v[16:31]
	ds_read_b128 v[64:67], v68 offset:32768
	ds_read_b128 v[72:75], v68 offset:34816
	ds_read_b128 v[76:79], v69 offset:40960
	ds_read_b128 v[80:83], v69 offset:43008
	ds_read_b128 v[84:87], v70 offset:32768
	ds_read_b128 v[88:91], v70 offset:34816
	ds_read_b128 v[92:95], v71 offset:40960
	ds_read_b128 v[152:155], v71 offset:43008
	s_waitcnt lgkmcnt(0)
	v_mfma_f32_32x32x16_bf16 v[32:47], v[64:67], v[76:79], v[32:47]
	s_waitcnt vmcnt(0)
	s_waitcnt lgkmcnt(0)
	s_barrier
	v_mfma_f32_32x32x16_bf16 v[48:63], v[64:67], v[80:83], v[48:63]
	v_mfma_f32_32x32x16_bf16 v[0:15], v[72:75], v[76:79], v[0:15]
	v_mfma_f32_32x32x16_bf16 v[16:31], v[72:75], v[80:83], v[16:31]
	v_mfma_f32_32x32x16_bf16 v[32:47], v[84:87], v[92:95], v[32:47]
	v_mfma_f32_32x32x16_bf16 v[48:63], v[84:87], v[152:155], v[48:63]
	v_mfma_f32_32x32x16_bf16 v[0:15], v[88:91], v[92:95], v[0:15]
	v_mfma_f32_32x32x16_bf16 v[16:31], v[88:91], v[152:155], v[16:31]
	ds_read_b128 v[64:67], v68 offset:49152
	ds_read_b128 v[72:75], v68 offset:51200
	ds_read_b128 v[76:79], v69 offset:57344
	ds_read_b128 v[80:83], v69 offset:59392
	ds_read_b128 v[84:87], v70 offset:49152
	ds_read_b128 v[88:91], v70 offset:51200
	ds_read_b128 v[92:95], v71 offset:57344
	ds_read_b128 v[68:71], v71 offset:59392
	s_lshl_b32 s21, s0, 7
	s_add_i32 s1, s21, 0xfffff000
	s_lshr_b32 s1, s1, 10
	s_add_i32 s1, s1, 1
	s_cmp_gt_i32 s0, 31
	s_cselect_b32 s0, s1, 0
	s_mul_i32 s1, s12, 3
	s_add_i32 s0, s0, s1
	s_waitcnt lgkmcnt(0)
	v_mfma_f32_32x32x16_bf16 v[48:63], v[64:67], v[80:83], v[48:63]
	s_mul_hi_u32 s1, s0, 0x6000
	s_mulk_i32 s0, 0x6000
	s_add_u32 s22, s16, s0
	s_addc_u32 s23, s17, s1
	s_movk_i32 s0, 0x2000
	s_lshl_b32 s30, s20, 2
	s_waitcnt lgkmcnt(0)
	v_mfma_f32_32x32x16_bf16 v[16:31], v[72:75], v[80:83], v[16:31]
	s_barrier
	v_add_u32_e32 v186, s21, v191
	v_ashrrev_i32_e32 v187, 31, v186
	v_lshl_add_u64 v[156:157], v[102:103], 0, s[30:31]
	v_lshlrev_b64 v[188:189], 12, v[186:187]
	v_add_u32_e32 v182, s21, v192
	v_ashrrev_i32_e32 v183, 31, v182
	v_mfma_f32_32x32x16_bf16 v[32:47], v[64:67], v[76:79], v[32:47]
	v_or_b32_e32 v64, s20, v190
	v_lshlrev_b32_e32 v64, 2, v64
	v_mov_b32_e32 v65, v117
	v_lshl_add_u64 v[64:65], s[22:23], 0, v[64:65]
	v_lshl_add_u64 v[66:67], v[64:65], 0, s[44:45]
	v_add_co_u32_e64 v64, s[0:1], s0, v64
	v_mfma_f32_32x32x16_bf16 v[48:63], v[84:87], v[68:71], v[48:63]
	s_nop 0
	v_addc_co_u32_e64 v65, s[0:1], 0, v65, s[0:1]
	s_add_u32 s0, s22, s30
	s_addc_u32 s1, s23, 0
	global_load_dword v137, v[64:65], off
	global_load_dword v139, v[66:67], off offset:128
	v_lshl_add_u64 v[64:65], v[104:105], 0, s[30:31]
	global_load_dwordx4 v[64:67], v[64:65], off
	v_mfma_f32_32x32x16_bf16 v[16:31], v[88:91], v[68:71], v[16:31]
	v_lshl_add_u64 v[68:69], s[0:1], 0, v[116:117]
	s_movk_i32 s0, 0x4000
	v_add_co_u32_e64 v68, s[0:1], s0, v68
	v_add_u32_e32 v178, s21, v193
	s_nop 0
	v_addc_co_u32_e64 v69, s[0:1], 0, v69, s[0:1]
	global_load_dwordx4 v[68:71], v[68:69], off
	v_mfma_f32_32x32x16_bf16 v[0:15], v[72:75], v[76:79], v[0:15]
	v_lshlrev_b64 v[184:185], 12, v[182:183]
	v_ashrrev_i32_e32 v179, 31, v178
	v_add_u32_e32 v174, s21, v194
	v_lshlrev_b64 v[180:181], 12, v[178:179]
	v_ashrrev_i32_e32 v175, 31, v174
	v_add_u32_e32 v170, s21, v195
	v_lshlrev_b64 v[176:177], 12, v[174:175]
	v_mfma_f32_32x32x16_bf16 v[32:47], v[84:87], v[92:95], v[32:47]
	v_ashrrev_i32_e32 v171, 31, v170
	v_add_u32_e32 v166, s21, v196
	v_lshlrev_b64 v[172:173], 12, v[170:171]
	v_ashrrev_i32_e32 v167, 31, v166
	v_add_u32_e32 v162, s21, v197
	v_lshlrev_b64 v[168:169], 12, v[166:167]
	v_ashrrev_i32_e32 v163, 31, v162
	v_mfma_f32_32x32x16_bf16 v[0:15], v[88:91], v[92:95], v[0:15]
	v_add_u32_e32 v158, s21, v198
	v_lshlrev_b64 v[164:165], 12, v[162:163]
	v_ashrrev_i32_e32 v159, 31, v158
	v_lshlrev_b64 v[160:161], 12, v[158:159]
	v_add_u32_e32 v141, 0x400, v199
	v_add_u32_e32 v143, 0x1000, v199
	v_add_u32_e32 v145, 0x1400, v199
	v_add_u32_e32 v147, 0x2000, v199
	v_add_u32_e32 v149, 0x2400, v199
	v_add_u32_e32 v151, 0x3000, v199
	v_add_u32_e32 v209, 0x3200, v199
	v_add_u32_e32 v210, 0x3400, v199
	v_add_u32_e32 v211, 0x3600, v199
	v_mov_b32_e32 v107, v117
	v_mov_b32_e32 v109, v117
	s_waitcnt vmcnt(0)
	v_mul_f32_e32 v32, v32, v137
	v_mul_f32_e32 v48, v48, v139
	ds_write2_b32 v199, v32, v48 offset1:32
	v_mul_f32_e32 v32, v33, v137
	v_mul_f32_e32 v33, v49, v139
	ds_write2_b32 v199, v32, v33 offset0:132 offset1:164
	v_mul_f32_e32 v32, v34, v137
	v_mul_f32_e32 v33, v50, v139
	ds_write2_b32 v141, v32, v33 offset0:8 offset1:40
	v_mul_f32_e32 v32, v35, v137
	v_mul_f32_e32 v33, v51, v139
	ds_write2_b32 v141, v32, v33 offset0:140 offset1:172
	v_pk_add_f32 v[68:69], v[68:69], 1.0 op_sel_hi:[1,0]
	v_pk_add_f32 v[70:71], v[70:71], 1.0 op_sel_hi:[1,0]
	v_pk_mul_f32 v[152:153], v[64:65], v[68:69]
	v_lshl_add_u64 v[64:65], v[156:157], 0, v[188:189]
	global_load_dwordx4 v[92:95], v[64:65], off
	v_lshl_add_u64 v[64:65], v[156:157], 0, v[184:185]
	global_load_dwordx4 v[88:91], v[64:65], off
	v_lshl_add_u64 v[64:65], v[156:157], 0, v[180:181]
	global_load_dwordx4 v[84:87], v[64:65], off
	v_lshl_add_u64 v[64:65], v[156:157], 0, v[176:177]
	global_load_dwordx4 v[80:83], v[64:65], off
	v_lshl_add_u64 v[64:65], v[156:157], 0, v[172:173]
	global_load_dwordx4 v[76:79], v[64:65], off
	v_lshl_add_u64 v[64:65], v[156:157], 0, v[168:169]
	global_load_dwordx4 v[72:75], v[64:65], off
	v_lshl_add_u64 v[64:65], v[156:157], 0, v[164:165]
	v_pk_mul_f32 v[154:155], v[66:67], v[70:71]
	global_load_dwordx4 v[68:71], v[64:65], off
	v_lshl_add_u64 v[64:65], v[156:157], 0, v[160:161]
	global_load_dwordx4 v[64:67], v[64:65], off
	v_mul_f32_e32 v32, v36, v137
	v_mul_f32_e32 v33, v52, v139
	ds_write2_b32 v143, v32, v33 offset0:32 offset1:64
	v_mul_f32_e32 v32, v37, v137
	v_mul_f32_e32 v33, v53, v139
	ds_write2_b32 v143, v32, v33 offset0:164 offset1:196
	v_mul_f32_e32 v32, v38, v137
	v_mul_f32_e32 v33, v54, v139
	ds_write2_b32 v145, v32, v33 offset0:40 offset1:72
	v_mul_f32_e32 v32, v39, v137
	v_mul_f32_e32 v33, v55, v139
	ds_write2_b32 v145, v32, v33 offset0:172 offset1:204
	v_mul_f32_e32 v32, v40, v137
	v_mul_f32_e32 v33, v56, v139
	ds_write2_b32 v147, v32, v33 offset0:64 offset1:96
	v_mul_f32_e32 v32, v41, v137
	v_mul_f32_e32 v33, v57, v139
	ds_write2_b32 v147, v32, v33 offset0:196 offset1:228
	v_mul_f32_e32 v32, v42, v137
	v_mul_f32_e32 v33, v58, v139
	ds_write2_b32 v149, v32, v33 offset0:72 offset1:104
	v_mul_f32_e32 v32, v43, v137
	v_mul_f32_e32 v33, v59, v139
	ds_write2_b32 v149, v32, v33 offset0:204 offset1:236
	v_mul_f32_e32 v32, v44, v137
	v_mul_f32_e32 v33, v60, v139
	ds_write2_b32 v151, v32, v33 offset0:96 offset1:128
	v_mul_f32_e32 v32, v45, v137
	v_mul_f32_e32 v33, v61, v139
	ds_write2_b32 v209, v32, v33 offset0:100 offset1:132
	v_mul_f32_e32 v32, v46, v137
	v_mul_f32_e32 v33, v62, v139
	ds_write2_b32 v210, v32, v33 offset0:104 offset1:136
	v_mul_f32_e32 v32, v47, v137
	v_mul_f32_e32 v33, v63, v139
	ds_write2_b32 v211, v32, v33 offset0:108 offset1:140
	s_waitcnt lgkmcnt(0)
	s_barrier
	ds_read_b128 v[32:35], v208
	v_lshl_add_u64 v[36:37], s[46:47], 0, v[188:189]
	v_lshl_add_u64 v[36:37], v[36:37], 0, s[30:31]
	v_lshl_add_u64 v[36:37], v[36:37], 0, v[116:117]
	v_or_b32_e32 v40, s20, v100
	v_lshlrev_b32_e32 v40, 8, v40
	v_and_b32_e32 v60, 0x3e000, v40
	v_mov_b32_e32 v61, v117
	s_waitcnt vmcnt(7) lgkmcnt(0)
	v_pk_add_f32 v[34:35], v[94:95], v[34:35]
	v_pk_add_f32 v[32:33], v[92:93], v[32:33]
	global_store_dwordx4 v[36:37], v[32:35], off
	v_pk_mul_f32 v[38:39], v[152:153], v[32:33]
	v_pk_mul_f32 v[36:37], v[154:155], v[34:35]
	v_mul_f32_e32 v33, v33, v33
	v_fmac_f32_e32 v33, v32, v32
	v_and_b32_e32 v32, 64, v213
	v_fmac_f32_e32 v33, v34, v34
	v_add_u32_e32 v34, 64, v32
	v_xor_b32_e32 v32, 16, v213
	v_cmp_lt_i32_e64 s[0:1], v32, v34
	v_fmac_f32_e32 v33, v35, v35
	v_cvt_pk_bf16_f32 v38, v38, v39
	v_cndmask_b32_e64 v32, v213, v32, s[0:1]
	v_lshlrev_b32_e32 v92, 2, v32
	ds_bpermute_b32 v32, v92, v33
	v_cvt_pk_bf16_f32 v39, v36, v37
	v_ashrrev_i32_e32 v36, 7, v186
	v_ashrrev_i32_e32 v37, 31, v36
	v_lshlrev_b64 v[36:37], 18, v[36:37]
	s_waitcnt lgkmcnt(0)
	v_add_f32_e32 v32, v33, v32
	v_xor_b32_e32 v33, 8, v213
	v_cmp_lt_i32_e64 s[0:1], v33, v34
	v_lshl_add_u64 v[36:37], s[10:11], 0, v[36:37]
	v_lshl_add_u64 v[36:37], v[36:37], 0, v[60:61]
	v_cndmask_b32_e64 v33, v213, v33, s[0:1]
	v_lshlrev_b32_e32 v93, 2, v33
	ds_bpermute_b32 v33, v93, v32
	v_lshl_add_u64 v[36:37], v[36:37], 0, v[106:107]
	v_lshl_add_u64 v[36:37], v[36:37], 0, v[108:109]
	global_store_dwordx2 v[36:37], v[38:39], off
	s_waitcnt lgkmcnt(0)
	v_add_f32_e32 v32, v32, v33
	v_xor_b32_e32 v33, 4, v213
	v_cmp_lt_i32_e64 s[0:1], v33, v34
	s_nop 1
	v_cndmask_b32_e64 v33, v213, v33, s[0:1]
	v_lshlrev_b32_e32 v94, 2, v33
	ds_bpermute_b32 v33, v94, v32
	s_waitcnt lgkmcnt(0)
	v_add_f32_e32 v32, v32, v33
	v_xor_b32_e32 v33, 2, v213
	v_cmp_lt_i32_e64 s[0:1], v33, v34
	s_nop 1
	v_cndmask_b32_e64 v33, v213, v33, s[0:1]
	v_lshlrev_b32_e32 v95, 2, v33
	ds_bpermute_b32 v33, v95, v32
	s_waitcnt lgkmcnt(0)
	v_add_f32_e32 v32, v32, v33
	v_xor_b32_e32 v33, 1, v213
	v_cmp_lt_i32_e64 s[0:1], v33, v34
	s_nop 1
	v_cndmask_b32_e64 v33, v213, v33, s[0:1]
	v_lshlrev_b32_e32 v107, 2, v33
	ds_bpermute_b32 v33, v107, v32
	s_and_saveexec_b64 s[0:1], vcc
	s_cbranch_execz .LBB0_150
	s_waitcnt lgkmcnt(0)
	v_add_f32_e32 v32, v32, v33
	v_fma_f32 v32, v32, s75, 0.5
	v_cvt_u32_f32_e32 v34, v32
	v_lshl_add_u64 v[32:33], v[186:187], 2, s[8:9]
	global_atomic_add v[32:33], v34, off

.LBB0_214:
	s_cmpk_gt_i32 s74, 0x17f
	s_cbranch_scc1 .Lsig_done
	s_waitcnt vmcnt(0)
	s_barrier
	v_cmp_eq_u32_e64 s[98:99], 0, v124
	s_and_saveexec_b64 s[18:19], s[98:99]
	s_cbranch_execz .Lsig_skip
	s_lshr_b32 s98, s74, 6
	s_lshl_b32 s98, s98, 3
	s_and_b32 s99, s74, 7
	s_or_b32 s98, s98, s99
	s_lshl_b32 s98, s98, 2
	s_addk_i32 s98, 0x100
	v_mov_b32_e32 v64, s98
	global_load_dword v65, v64, s[4:5] sc1
	s_getreg_b32 s99, hwreg(HW_REG_XCC_ID, 0, 4)
	s_lshl_b32 s99, s99, 2
	s_lshl_b32 s99, 8, s99
	s_waitcnt vmcnt(0)
	v_readfirstlane_b32 s98, v65
	s_cmp_eq_u32 s98, s99
	s_cbranch_scc1 .Lsig_norel
	buffer_wbl2 sc1
	s_waitcnt vmcnt(0)
.Lsig_norel:
	s_lshr_b32 s98, s74, 6
	s_lshl_b32 s98, s98, 3
	s_and_b32 s99, s74, 7
	s_or_b32 s98, s98, s99
	s_lshl_b32 s98, s98, 2
	s_lshl_b32 s99, s12, 8
	s_add_i32 s98, s98, s99
	s_addk_i32 s98, 0x1404
	v_mov_b32_e32 v64, s98
	v_mov_b32_e32 v65, 1
	global_atomic_add v64, v65, s[4:5]
.Lsig_skip:
	s_or_b64 exec, exec, s[18:19]
.Lsig_done:
	s_mov_b64 s[0:1], 0
	v_mov_b32_e32 v242, v219
	v_mov_b32_e32 v219, v221
	v_mov_b32_e32 v221, 0xffffe400

.Llong21:
	s_getpc_b64 s[98:99]

.Lchk_skip:
	s_add_i32 s99, s6, -3
	s_cmp_lt_i32 s99, 0
	s_cbranch_scc1 .LBB0_509
	s_mul_i32 s98, s99, 37
	s_lshr_b32 s98, s98, 8
	s_mul_i32 s98, s98, 7
	s_sub_i32 s99, s99, s98
	s_cmp_eq_u32 s99, 3
	s_cbranch_scc0 .LBB0_509
	s_waitcnt vmcnt(0) lgkmcnt(0)
	s_barrier
	s_mov_b64 s[0:1], 0
	s_branch .Llong21

.Lbar_follow:
	global_load_dword v0, v117, s[8:9] sc1
	s_waitcnt vmcnt(0)
	v_cmp_eq_u32_e32 vcc, v0, v1
	s_and_saveexec_b64 s[8:9], vcc
	s_cbranch_execz .LBB0_540
	s_mov_b32 s20, 1
	s_mov_b64 s[10:11], 0
	s_branch .LBB0_531

.LBB0_542:
	v_mov_b32_e32 v5, v1
	s_mov_b64 s[2:3], exec
	buffer_wbl2 sc1
	s_waitcnt lgkmcnt(0)
	s_waitcnt vmcnt(0)
	buffer_inv sc1
	v_mbcnt_lo_u32_b32 v1, s2, 0
	v_mbcnt_hi_u32_b32 v1, s3, v1
	v_cmp_eq_u32_e32 vcc, 0, v1
	s_and_saveexec_b64 s[8:9], vcc
	s_cbranch_execz .LBB0_544
	s_bcnt1_i32_b64 s2, s[2:3]
	v_mov_b32_e32 v2, s2
	v_readlane_b32 s2, v254, 42
	v_readlane_b32 s3, v254, 43
	s_nop 4
	global_atomic_add v2, v117, v2, s[2:3] sc0
.LBB0_544:
	s_or_b64 exec, exec, s[8:9]
	s_waitcnt vmcnt(0)
	v_readfirstlane_b32 s2, v2
	v_cvt_f32_u32_e32 v2, v0
	v_sub_u32_e32 v3, 0, v0
	v_add_u32_e32 v1, s2, v1
	v_readlane_b32 s2, v254, 44
	v_rcp_iflag_f32_e32 v2, v2
	v_readlane_b32 s3, v254, 45
	s_mov_b64 s[8:9], -1
	v_mul_f32_e32 v2, 0x4f7ffffe, v2
	v_cvt_u32_f32_e32 v2, v2
	v_mul_lo_u32 v3, v3, v2
	v_mul_hi_u32 v3, v2, v3
	v_add_u32_e32 v2, v2, v3
	v_mul_hi_u32 v2, v1, v2
	v_mul_lo_u32 v3, v2, v0
	v_sub_u32_e32 v3, v1, v3
	v_cmp_ge_u32_e32 vcc, v3, v0
	v_add_u32_e32 v4, 1, v2
	v_add_u32_e32 v1, 1, v1
	v_cndmask_b32_e32 v2, v2, v4, vcc
	v_sub_u32_e32 v4, v3, v0
	v_cndmask_b32_e32 v3, v3, v4, vcc
	v_cmp_ge_u32_e32 vcc, v3, v0
	v_add_u32_e32 v3, 1, v2
	s_nop 0
	v_cndmask_b32_e32 v2, v2, v3, vcc
	v_mul_lo_u32 v3, v0, v2
	v_add_u32_e32 v0, v3, v0
	v_cmp_ne_u32_e32 vcc, v1, v0
	s_and_saveexec_b64 s[2:3], vcc
	s_cbranch_execz .Lbar_last
	v_mov_b32_e32 v1, v5
	s_mov_b64 s[2:3], 0
	v_readlane_b32 s8, v254, 40
	v_readlane_b32 s9, v254, 41
	s_nop 4
	s_branch .Lbar_follow
.Lbar_last:
	s_or_b64 exec, exec, s[2:3]
	v_mov_b32_e32 v0, 0x2400
	v_mov_b32_e32 v2, 1
	global_atomic_add v0, v2, s[4:5]
	v_add_u32_e32 v0, 0x100, v0
	global_atomic_add v0, v2, s[4:5]
	v_add_u32_e32 v0, 0x100, v0
	global_atomic_add v0, v2, s[4:5]
	v_add_u32_e32 v0, 0x100, v0
	global_atomic_add v0, v2, s[4:5]
	v_add_u32_e32 v0, 0x100, v0
	global_atomic_add v0, v2, s[4:5]
	v_add_u32_e32 v0, 0x100, v0
	global_atomic_add v0, v2, s[4:5]
	v_add_u32_e32 v0, 0x100, v0
	global_atomic_add v0, v2, s[4:5]
	v_add_u32_e32 v0, 0x100, v0
	global_atomic_add v0, v2, s[4:5]
	v_add_u32_e32 v0, 0x100, v0
	global_atomic_add v0, v2, s[4:5]
	v_add_u32_e32 v0, 0x100, v0
	global_atomic_add v0, v2, s[4:5]
	v_add_u32_e32 v0, 0x100, v0
	global_atomic_add v0, v2, s[4:5]
	v_add_u32_e32 v0, 0x100, v0
	global_atomic_add v0, v2, s[4:5]
	v_add_u32_e32 v0, 0x100, v0
	global_atomic_add v0, v2, s[4:5]
	v_add_u32_e32 v0, 0x100, v0
	global_atomic_add v0, v2, s[4:5]
	v_add_u32_e32 v0, 0x100, v0
	global_atomic_add v0, v2, s[4:5]
	v_add_u32_e32 v0, 0x100, v0
	global_atomic_add v0, v2, s[4:5]
	s_mov_b64 s[8:9], 0
	s_getpc_b64 s[98:99]
